# GEMM phases 10/13/18: tiles of the partial last round split into four 256x32 column slices (narrow units) spread over all workgroups
# speedup vs baseline: 1.1685x; 1.0065x over previous
; #define PH(n, sync_) if (plo <= (n) && (n) <= phi) { if ((n) > plo && (sync_)) { if ((n) == 1) { grid.sync(); xb = xcd_barrier_post((unsigned*)(ws + O_XBAR), (volatile LAS unsigned*)&xb_words); } else xcd_barrier(xb); }
; template <int EPI>
; __device__ __forceinline__ void gemm_phase(const Params& p, const u16* __restrict__ A, int lda, const u16* __restrict__ BT, int ldb,
;                            int K, int N, u16* __restrict__ outb, int ldo, int resid_in, int boff) {
;     ...
;   const int lrow = tid >> 3, lch = tid & 7;
;   const int NT = N / 128;
;   const int tiles = (MT / 256) * NT;
;   const int KTALL = K / 64;
;   float* part = (float*)(p.ws + O_PART);
;   int bstart = (int)blockIdx.x - boff;
;   if (bstart < 0) bstart += gridDim.x;
;   const size_t a64 = (size_t)64 * lda, b64 = (size_t)64 * ldb;
;   const int G = gridDim.x;
;   int t_full = tiles, split = 1;
;   if (EPI == EPI_RES) {
;     const int tail = tiles % G;
;     if (tail > 0 && (G % tail) == 0 && (KTALL % (G / tail)) == 0) { t_full = tiles - tail; const int smax = (KTALL >= 64) ? 8 : 4; split = (G / tail) > smax ? smax : (G / tail); }
;   }
;   const int units = t_full + (tiles - t_full) * split;
; __global__ void __launch_bounds__(512) mega(Params p, int plo, int phi) {
;     ...
;   PH(10, 1) gemm_phase<EPI_FF1>(p, WSB(O_XB), 1024, WSB(O_WF10), 1024, 1024, 4096, WSO(O_H), 4096, 0, 0); PHEND
.Lgm_par10:
	s_add_u32 s16, s96, 0x2f08100
	s_addc_u32 s17, s97, 0
	s_add_u32 s20, s96, 0x780000
	s_addc_u32 s21, s97, 0
	s_add_u32 s22, s96, 0x7108100
	s_addc_u32 s23, s97, 0
	s_movk_i32 s24, 0x2000
	s_mov_b32 s25, 32
	s_mov_b32 s26, 0x8000000
	s_mov_b32 s27, 1
	s_movk_i32 s28, 0x800
	s_movk_i32 s29, 0x800
	s_mov_b32 s30, 1
	s_movk_i32 s38, 0x900
	s_mov_b32 s39, 16
	s_mov_b32 s44, 0
	s_mov_b32 s45, 11
	s_mov_b32 s46, 11
	s_branch .Lgm_common

; #define PH(n, sync_) if (plo <= (n) && (n) <= phi) { if ((n) > plo && (sync_)) { if ((n) == 1) { grid.sync(); xb = xcd_barrier_post((unsigned*)(ws + O_XBAR), (volatile LAS unsigned*)&xb_words); } else xcd_barrier(xb); }
; template <int EPI>
; __device__ __forceinline__ void gemm_phase(const Params& p, const u16* __restrict__ A, int lda, const u16* __restrict__ BT, int ldb,
;                            int K, int N, u16* __restrict__ outb, int ldo, int resid_in, int boff) {
;     ...
;   const int lrow = tid >> 3, lch = tid & 7;
;   const int NT = N / 128;
;   const int tiles = (MT / 256) * NT;
;   const int KTALL = K / 64;
;   float* part = (float*)(p.ws + O_PART);
;   int bstart = (int)blockIdx.x - boff;
;   if (bstart < 0) bstart += gridDim.x;
;   const size_t a64 = (size_t)64 * lda, b64 = (size_t)64 * ldb;
;   const int G = gridDim.x;
;   int t_full = tiles, split = 1;
;   if (EPI == EPI_RES) {
;     const int tail = tiles % G;
;     if (tail > 0 && (G % tail) == 0 && (KTALL % (G / tail)) == 0) { t_full = tiles - tail; const int smax = (KTALL >= 64) ? 8 : 4; split = (G / tail) > smax ? smax : (G / tail); }
;   }
;   const int units = t_full + (tiles - t_full) * split;
; __global__ void __launch_bounds__(512) mega(Params p, int plo, int phi) {
;     ...
;   PH(13, 1) gemm_phase<EPI_SCALE>(p, WSB(O_XB), 1024, WSB(O_WIN1), 1024, 1024, 2048, WSO(O_P), 2048, 0, 0); PHEND
.Lgm_par13:
	s_add_u32 s16, s96, 0x2f08100
	s_addc_u32 s17, s97, 0
	s_add_u32 s20, s96, 0x1780000
	s_addc_u32 s21, s97, 0
	s_add_u32 s22, s96, 0x7108100
	s_addc_u32 s23, s97, 0
	s_movk_i32 s24, 0x1000
	s_mov_b32 s25, 16
	s_mov_b32 s26, 0x10000000
	s_mov_b32 s27, 2
	s_movk_i32 s28, 0x400
	s_movk_i32 s29, 0x400
	s_mov_b32 s30, 0
	s_movk_i32 s38, 0x480
	s_mov_b32 s39, 16
	s_mov_b32 s44, 0
	s_mov_b32 s45, 11
	s_mov_b32 s46, 11
	s_branch .Lgm_common

; #define PH(n, sync_) if (plo <= (n) && (n) <= phi) { if ((n) > plo && (sync_)) { if ((n) == 1) { grid.sync(); xb = xcd_barrier_post((unsigned*)(ws + O_XBAR), (volatile LAS unsigned*)&xb_words); } else xcd_barrier(xb); }
; template <int EPI>
; __device__ __forceinline__ void gemm_phase(const Params& p, const u16* __restrict__ A, int lda, const u16* __restrict__ BT, int ldb,
;                            int K, int N, u16* __restrict__ outb, int ldo, int resid_in, int boff) {
;     ...
;   const int lrow = tid >> 3, lch = tid & 7;
;   const int NT = N / 128;
;   const int tiles = (MT / 256) * NT;
;   const int KTALL = K / 64;
;   float* part = (float*)(p.ws + O_PART);
;   int bstart = (int)blockIdx.x - boff;
;   if (bstart < 0) bstart += gridDim.x;
;   const size_t a64 = (size_t)64 * lda, b64 = (size_t)64 * ldb;
;   const int G = gridDim.x;
;   int t_full = tiles, split = 1;
;   if (EPI == EPI_RES) {
;     const int tail = tiles % G;
;     if (tail > 0 && (G % tail) == 0 && (KTALL % (G / tail)) == 0) { t_full = tiles - tail; const int smax = (KTALL >= 64) ? 8 : 4; split = (G / tail) > smax ? smax : (G / tail); }
;   }
;   const int units = t_full + (tiles - t_full) * split;
; __global__ void __launch_bounds__(512) mega(Params p, int plo, int phi) {
;     ...
;   PH(18, 1) gemm_phase<EPI_FF1>(p, WSB(O_XB), 1024, WSB(O_WF11), 1024, 1024, 4096, WSO(O_H), 4096, 0, 0); PHEND
.Lgm_par18:
	s_add_u32 s16, s96, 0x2f08100
	s_addc_u32 s17, s97, 0
	s_add_u32 s20, s96, 0x1d80000
	s_addc_u32 s21, s97, 0
	s_add_u32 s22, s96, 0x7108100
	s_addc_u32 s23, s97, 0
	s_movk_i32 s24, 0x2000
	s_mov_b32 s25, 32
	s_mov_b32 s26, 0x8000000
	s_mov_b32 s27, 1
	s_movk_i32 s28, 0x800
	s_movk_i32 s29, 0x800
	s_mov_b32 s30, 1
	s_movk_i32 s38, 0x900
	s_mov_b32 s39, 16
	s_mov_b32 s44, 0
	s_mov_b32 s45, 11
	s_mov_b32 s46, 11
	s_branch .Lgm_common

; template <int EPI>
; __device__ __forceinline__ void gemm_phase(const Params& p, const u16* __restrict__ A, int lda, const u16* __restrict__ BT, int ldb,
;                            int K, int N, u16* __restrict__ outb, int ldo, int resid_in, int boff) {
;     ...
;   for (int un = bstart; un < units; un += G) {
;     int tl = un, kbeg = 0, KT = KTALL;
;     bool part_unit = false;
;     if (un >= t_full) { const int v = un - t_full; tl = t_full + v / split; KT = KTALL / split; kbeg = (v % split) * KT; part_unit = true; }
;     int mt = tl / NT, nt = tl % NT;
;     if (EPI == EPI_RES && NT == 8 && G == 256 && !part_unit) {
;       const int rr = tl >> 8, bb = tl & 255;
;       const int xx = bb & 7, jj = bb >> 3;
;       mt = rr * 32 + xx * 4 + (jj >> 3);
;       nt = jj & 7;
;     } else if ((EPI == EPI_FF1 || EPI == EPI_SCALE) && G == 256 && (NT == 32 || NT == 16) && tl < (tiles & ~255)) {
;       const int rr = tl >> 8, bb = tl & 255;
;       const int xx = bb & 7, jj = bb >> 3;
;       if (NT == 32) { mt = rr * 8 + (xx >> 2) * 4 + (jj >> 3); nt = (xx & 3) * 8 + (jj & 7); }
;       else { mt = rr * 16 + (xx >> 1) * 4 + (jj >> 3); nt = (xx & 1) * 8 + (jj & 7); }
;     }
.Lgc_unit:
	s_cmp_ge_u32 s5, s38
	s_cbranch_scc1 .Lgm_exit
	s_mov_b32 s47, 0
	s_cmp_ge_u32 s5, s28
	s_cbranch_scc1 .Lgm_split_c
	s_mov_b32 s8, 0
	s_mov_b32 s9, s39
	s_mov_b32 s10, 0
	s_cmp_eq_u32 s27, 0
	s_cbranch_scc1 .Lgm_plain_c
	s_cmp_ge_u32 s5, s29
	s_cbranch_scc1 .Lgm_plain_c
	s_lshr_b32 s6, s5, 8
	s_and_b32 s7, s5, 0xff
	s_and_b32 s36, s7, 7
	s_lshr_b32 s37, s7, 3
	s_cmp_eq_u32 s27, 3
	s_cbranch_scc1 .Lgm_map8_c
	s_cmp_eq_u32 s27, 1
	s_cbranch_scc0 .Lgm_map16_c
	s_lshl_b32 s6, s6, 3
	s_lshr_b32 s7, s36, 2
	s_lshl_b32 s7, s7, 2
	s_add_u32 s6, s6, s7
	s_lshr_b32 s7, s37, 3
	s_add_u32 s6, s6, s7
	s_and_b32 s7, s36, 3
	s_lshl_b32 s7, s7, 3
	s_and_b32 s37, s37, 7
	s_add_u32 s7, s7, s37
	s_branch .Lgm_dec_done_c

; template <int EPI>
; __device__ __forceinline__ void gemm_phase(const Params& p, const u16* __restrict__ A, int lda, const u16* __restrict__ BT, int ldb,
;                            int K, int N, u16* __restrict__ outb, int ldo, int resid_in, int boff) {
;     ...
;   for (int un = bstart; un < units; un += G) {
;     int tl = un, kbeg = 0, KT = KTALL;
;     bool part_unit = false;
;     if (un >= t_full) { const int v = un - t_full; tl = t_full + v / split; KT = KTALL / split; kbeg = (v % split) * KT; part_unit = true; }
;     int mt = tl / NT, nt = tl % NT;
.Lgm_split_c:
	s_cmp_eq_u32 s30, 3
	s_cbranch_scc1 .Lgm_splitk_c
	s_sub_u32 s36, s5, s28
	s_and_b32 s47, s36, 3
	s_lshl_b32 s47, s47, 5
	s_lshr_b32 s36, s36, 2
	s_add_u32 s36, s36, s28
	s_mul_hi_u32 s6, s36, s26
	s_mul_i32 s7, s6, s25
	s_sub_u32 s7, s36, s7
	s_mov_b32 s8, 0
	s_mov_b32 s9, s39
	s_mov_b32 s10, 2
	s_branch .Lgm_dec_done_c

; #define RAW_BARRIER() do { asm volatile("s_waitcnt lgkmcnt(0)" ::: "memory"); __builtin_amdgcn_s_barrier(); asm volatile("" ::: "memory"); } while (0)
; template <int EPI>
; __device__ __forceinline__ void gemm_phase(const Params& p, const u16* __restrict__ A, int lda, const u16* __restrict__ BT, int ldb,
;                            int K, int N, u16* __restrict__ outb, int ldo, int resid_in, int boff) {
;     ...
;     __syncthreads();
;     WRITEX(0);
;     if (KT > 2) LOADX(2);
;     RAW_BARRIER();
;     for (int kt = 0; kt < KT; kt += 2) {
;       if (kt + 1 < KT) WRITEY(1);
;       if (kt + 3 < KT) LOADY(kt + 3);
;       COMPUTE(0);
;       RAW_BARRIER();
.Lgm_dec_done_c:
	s_sub_u32 s18, s9, 1
	s_cmp_eq_u32 s10, 1
	s_cbranch_scc1 .Lgc_unitN
	s_cmp_eq_u32 s10, 2
	s_cbranch_scc1 .Lgc_unitW
	ds_read_b128 v[130:133], v226
	ds_read_b128 v[146:149], v228
	ds_read_b128 v[150:153], v228 offset:2048
	ds_read_b128 v[154:157], v228 offset:4096
	ds_read_b128 v[158:161], v228 offset:6144
	ds_read_b128 v[162:165], v228 offset:8192
	ds_read_b128 v[166:169], v228 offset:10240
	ds_read_b128 v[170:173], v228 offset:12288
	ds_read_b128 v[174:177], v228 offset:14336
	ds_read_b128 v[134:137], v226 offset:2048
	ds_read_b128 v[138:141], v226 offset:4096
	ds_read_b128 v[142:145], v226 offset:6144
	s_waitcnt lgkmcnt(3)
	v_mfma_f32_16x16x32_bf16 v[0:3], v[146:149], v[130:133], 0
	ds_read_b128 v[178:181], v227
	v_mfma_f32_16x16x32_bf16 v[4:7], v[150:153], v[130:133], 0
	ds_read_b128 v[194:197], v229
	v_mfma_f32_16x16x32_bf16 v[8:11], v[154:157], v[130:133], 0
	ds_read_b128 v[198:201], v229 offset:2048
	v_mfma_f32_16x16x32_bf16 v[12:15], v[158:161], v[130:133], 0
	ds_read_b128 v[202:205], v229 offset:4096
	v_mfma_f32_16x16x32_bf16 v[16:19], v[162:165], v[130:133], 0
	ds_read_b128 v[206:209], v229 offset:6144
	v_mfma_f32_16x16x32_bf16 v[20:23], v[166:169], v[130:133], 0
	ds_read_b128 v[210:213], v229 offset:8192
	v_mfma_f32_16x16x32_bf16 v[24:27], v[170:173], v[130:133], 0
	ds_read_b128 v[214:217], v229 offset:10240
	v_mfma_f32_16x16x32_bf16 v[28:31], v[174:177], v[130:133], 0
	ds_read_b128 v[218:221], v229 offset:12288
	s_waitcnt lgkmcnt(10)
	v_mfma_f32_16x16x32_bf16 v[32:35], v[146:149], v[134:137], 0
	ds_read_b128 v[222:225], v229 offset:14336
	v_mfma_f32_16x16x32_bf16 v[36:39], v[150:153], v[134:137], 0
	ds_read_b128 v[182:185], v227 offset:2048
	v_mfma_f32_16x16x32_bf16 v[40:43], v[154:157], v[134:137], 0
	ds_read_b128 v[186:189], v227 offset:4096
	v_mfma_f32_16x16x32_bf16 v[44:47], v[158:161], v[134:137], 0
	ds_read_b128 v[190:193], v227 offset:6144
	v_mfma_f32_16x16x32_bf16 v[48:51], v[162:165], v[134:137], 0
	v_add_u32_e32 v226, s31, v226
	v_mfma_f32_16x16x32_bf16 v[52:55], v[166:169], v[134:137], 0
	v_add_u32_e32 v227, s31, v227
	v_mfma_f32_16x16x32_bf16 v[56:59], v[170:173], v[134:137], 0
	v_add_u32_e32 v228, s31, v228
	v_mfma_f32_16x16x32_bf16 v[60:63], v[174:177], v[134:137], 0
	v_add_u32_e32 v229, s31, v229
	s_waitcnt lgkmcnt(13)
	v_mfma_f32_16x16x32_bf16 v[64:67], v[146:149], v[138:141], 0
	v_mfma_f32_16x16x32_bf16 v[68:71], v[150:153], v[138:141], 0
	v_mfma_f32_16x16x32_bf16 v[72:75], v[154:157], v[138:141], 0
	v_mfma_f32_16x16x32_bf16 v[76:79], v[158:161], v[138:141], 0
	v_mfma_f32_16x16x32_bf16 v[80:83], v[162:165], v[138:141], 0
	v_mfma_f32_16x16x32_bf16 v[84:87], v[166:169], v[138:141], 0
	v_mfma_f32_16x16x32_bf16 v[88:91], v[170:173], v[138:141], 0
	v_mfma_f32_16x16x32_bf16 v[92:95], v[174:177], v[138:141], 0
	s_waitcnt lgkmcnt(12)
	v_mfma_f32_16x16x32_bf16 v[96:99], v[146:149], v[142:145], 0
	v_mfma_f32_16x16x32_bf16 v[100:103], v[150:153], v[142:145], 0
	v_mfma_f32_16x16x32_bf16 v[104:107], v[154:157], v[142:145], 0
	v_mfma_f32_16x16x32_bf16 v[108:111], v[158:161], v[142:145], 0
	v_mfma_f32_16x16x32_bf16 v[112:115], v[162:165], v[142:145], 0
	v_mfma_f32_16x16x32_bf16 v[116:119], v[166:169], v[142:145], 0
	v_mfma_f32_16x16x32_bf16 v[120:123], v[170:173], v[142:145], 0
	v_mfma_f32_16x16x32_bf16 v[124:127], v[174:177], v[142:145], 0
	s_add_u32 s13, s13, 1
	s_cmp_eq_u32 s13, 3
	s_cselect_b32 s13, 0, s13
	s_cmp_eq_u32 s13, 2
	s_cselect_b32 s31, s34, s35
	s_waitcnt lgkmcnt(0)
	s_barrier
	s_cmp_eq_u32 s18, 0
	s_cbranch_scc1 .Lgc_tailT

; template <int EPI> ...
;     ...
;     if (EPI == EPI_SCALE || EPI == EPI_PLAIN || EPI == EPI_FF1) {
; #pragma unroll
;       for (int i = 0; i < 16; i++) {
;         const int rl = rbase + (i & 3) + 8 * (i >> 2);
;         const int row = m0 + rl;
;         float v0 = acc0[i], v1 = acc1[i];
;         if (EPI != EPI_PLAIN) { float rs = sRs[rl]; v0 *= rs; v1 *= rs; }
;         if (EPI == EPI_FF1) { v0 = fmaxf(v0, 0.f); v1 = fmaxf(v1, 0.f); v0 *= v0; v1 *= v1; }
;         outb[(size_t)row * ldo + c0] = f2bf(v0);
;         outb[(size_t)row * ldo + c1] = f2bf(v1);
;       }
; template <int EPI>
; __device__ __forceinline__ void gemm_phase(const Params& p, const u16* __restrict__ A, int lda, const u16* __restrict__ BT, int ldb,
;                            int K, int N, u16* __restrict__ outb, int ldo, int resid_in, int boff) {
;     ...
;     const int c0 = n0 + wn * 64 + (lane & 31);
;     const int c1 = c0 + 32;
.Lgc_tailT:
	v_mfma_f32_16x16x32_bf16 v[0:3], v[194:197], v[178:181], v[0:3]
	v_mfma_f32_16x16x32_bf16 v[4:7], v[198:201], v[178:181], v[4:7]
	v_mfma_f32_16x16x32_bf16 v[8:11], v[202:205], v[178:181], v[8:11]
	v_mfma_f32_16x16x32_bf16 v[12:15], v[206:209], v[178:181], v[12:15]
	v_mfma_f32_16x16x32_bf16 v[16:19], v[210:213], v[178:181], v[16:19]
	v_mfma_f32_16x16x32_bf16 v[20:23], v[214:217], v[178:181], v[20:23]
	v_mfma_f32_16x16x32_bf16 v[24:27], v[218:221], v[178:181], v[24:27]
	v_mfma_f32_16x16x32_bf16 v[28:31], v[222:225], v[178:181], v[28:31]
	v_mfma_f32_16x16x32_bf16 v[32:35], v[194:197], v[182:185], v[32:35]
	v_mfma_f32_16x16x32_bf16 v[36:39], v[198:201], v[182:185], v[36:39]
	v_mfma_f32_16x16x32_bf16 v[40:43], v[202:205], v[182:185], v[40:43]
	v_mfma_f32_16x16x32_bf16 v[44:47], v[206:209], v[182:185], v[44:47]
	v_mfma_f32_16x16x32_bf16 v[48:51], v[210:213], v[182:185], v[48:51]
	v_mfma_f32_16x16x32_bf16 v[52:55], v[214:217], v[182:185], v[52:55]
	v_mfma_f32_16x16x32_bf16 v[56:59], v[218:221], v[182:185], v[56:59]
	v_mfma_f32_16x16x32_bf16 v[60:63], v[222:225], v[182:185], v[60:63]
	v_mfma_f32_16x16x32_bf16 v[64:67], v[194:197], v[186:189], v[64:67]
	v_mfma_f32_16x16x32_bf16 v[68:71], v[198:201], v[186:189], v[68:71]
	v_mfma_f32_16x16x32_bf16 v[72:75], v[202:205], v[186:189], v[72:75]
	v_mfma_f32_16x16x32_bf16 v[76:79], v[206:209], v[186:189], v[76:79]
	v_mfma_f32_16x16x32_bf16 v[80:83], v[210:213], v[186:189], v[80:83]
	v_mfma_f32_16x16x32_bf16 v[84:87], v[214:217], v[186:189], v[84:87]
	v_mfma_f32_16x16x32_bf16 v[88:91], v[218:221], v[186:189], v[88:91]
	v_mfma_f32_16x16x32_bf16 v[92:95], v[222:225], v[186:189], v[92:95]
	v_mfma_f32_16x16x32_bf16 v[96:99], v[194:197], v[190:193], v[96:99]
	v_mfma_f32_16x16x32_bf16 v[100:103], v[198:201], v[190:193], v[100:103]
	v_mfma_f32_16x16x32_bf16 v[104:107], v[202:205], v[190:193], v[104:107]
	v_mfma_f32_16x16x32_bf16 v[108:111], v[206:209], v[190:193], v[108:111]
	v_mfma_f32_16x16x32_bf16 v[112:115], v[210:213], v[190:193], v[112:115]
	v_mfma_f32_16x16x32_bf16 v[116:119], v[214:217], v[190:193], v[116:119]
	v_mfma_f32_16x16x32_bf16 v[120:123], v[218:221], v[190:193], v[120:123]
	v_mfma_f32_16x16x32_bf16 v[124:127], v[222:225], v[190:193], v[124:127]
	s_cmp_eq_u32 s30, 3
	s_cbranch_scc1 .Lgc_epi_res
	s_lshl_b32 s11, s6, 8
	s_lshl_b32 s12, s4, 6
	s_add_u32 s11, s11, s12
	v_add_u32_e32 v238, s11, v248
	v_mul_lo_u32 v230, v238, s24
	s_lshl_b32 s11, s7, 7
	s_add_u32 s11, s11, s47
	v_and_b32_e32 v239, 1, v249
	v_lshrrev_b32_e32 v240, 1, v249
	v_lshlrev_b32_e32 v239, 4, v239
	v_lshl_add_u32 v239, v240, 3, v239
	v_add_u32_e32 v239, s11, v239
	v_lshlrev_b32_e32 v239, 1, v239
	v_add_u32_e32 v230, v230, v239
	s_lshl_b32 s11, s24, 4
	v_add_u32_e32 v231, s11, v230
	v_add_u32_e32 v232, s11, v231
	v_add_u32_e32 v233, s11, v232
	s_nop 7
	s_cmp_eq_u32 s30, 4
	s_cbranch_scc1 .Lgm_norelu
	v_add_u32_e32 v239, s33, v242
	ds_read_b32 v234, v239
	ds_read_b32 v235, v239 offset:64
	ds_read_b32 v236, v239 offset:128
	ds_read_b32 v237, v239 offset:192
	s_waitcnt lgkmcnt(0)
	v_mul_f32_e32 v0, v0, v234
	v_mul_f32_e32 v1, v1, v234
	v_mul_f32_e32 v2, v2, v234
	v_mul_f32_e32 v3, v3, v234
	v_mul_f32_e32 v4, v4, v234
	v_mul_f32_e32 v5, v5, v234
	v_mul_f32_e32 v6, v6, v234
	v_mul_f32_e32 v7, v7, v234
	v_mul_f32_e32 v8, v8, v234
	v_mul_f32_e32 v9, v9, v234
	v_mul_f32_e32 v10, v10, v234
	v_mul_f32_e32 v11, v11, v234
	v_mul_f32_e32 v12, v12, v234
	v_mul_f32_e32 v13, v13, v234
	v_mul_f32_e32 v14, v14, v234
	v_mul_f32_e32 v15, v15, v234
	v_mul_f32_e32 v16, v16, v234
	v_mul_f32_e32 v17, v17, v234
	v_mul_f32_e32 v18, v18, v234
	v_mul_f32_e32 v19, v19, v234
	v_mul_f32_e32 v20, v20, v234
	v_mul_f32_e32 v21, v21, v234
	v_mul_f32_e32 v22, v22, v234
	v_mul_f32_e32 v23, v23, v234
	v_mul_f32_e32 v24, v24, v234
	v_mul_f32_e32 v25, v25, v234
	v_mul_f32_e32 v26, v26, v234
	v_mul_f32_e32 v27, v27, v234
	v_mul_f32_e32 v28, v28, v234
	v_mul_f32_e32 v29, v29, v234
	v_mul_f32_e32 v30, v30, v234
	v_mul_f32_e32 v31, v31, v234
	v_mul_f32_e32 v32, v32, v235
	v_mul_f32_e32 v33, v33, v235
	v_mul_f32_e32 v34, v34, v235
	v_mul_f32_e32 v35, v35, v235
	v_mul_f32_e32 v36, v36, v235
	v_mul_f32_e32 v37, v37, v235
	v_mul_f32_e32 v38, v38, v235
	v_mul_f32_e32 v39, v39, v235
	v_mul_f32_e32 v40, v40, v235
	v_mul_f32_e32 v41, v41, v235
	v_mul_f32_e32 v42, v42, v235
	v_mul_f32_e32 v43, v43, v235
	v_mul_f32_e32 v44, v44, v235
	v_mul_f32_e32 v45, v45, v235
	v_mul_f32_e32 v46, v46, v235
	v_mul_f32_e32 v47, v47, v235
	v_mul_f32_e32 v48, v48, v235
	v_mul_f32_e32 v49, v49, v235
	v_mul_f32_e32 v50, v50, v235
	v_mul_f32_e32 v51, v51, v235
	v_mul_f32_e32 v52, v52, v235
	v_mul_f32_e32 v53, v53, v235
	v_mul_f32_e32 v54, v54, v235
	v_mul_f32_e32 v55, v55, v235
	v_mul_f32_e32 v56, v56, v235
	v_mul_f32_e32 v57, v57, v235
	v_mul_f32_e32 v58, v58, v235
	v_mul_f32_e32 v59, v59, v235
	v_mul_f32_e32 v60, v60, v235
	v_mul_f32_e32 v61, v61, v235
	v_mul_f32_e32 v62, v62, v235
	v_mul_f32_e32 v63, v63, v235
	v_mul_f32_e32 v64, v64, v236
	v_mul_f32_e32 v65, v65, v236
	v_mul_f32_e32 v66, v66, v236
	v_mul_f32_e32 v67, v67, v236
	v_mul_f32_e32 v68, v68, v236
	v_mul_f32_e32 v69, v69, v236
	v_mul_f32_e32 v70, v70, v236
	v_mul_f32_e32 v71, v71, v236
	v_mul_f32_e32 v72, v72, v236
	v_mul_f32_e32 v73, v73, v236
	v_mul_f32_e32 v74, v74, v236
	v_mul_f32_e32 v75, v75, v236
	v_mul_f32_e32 v76, v76, v236
	v_mul_f32_e32 v77, v77, v236
	v_mul_f32_e32 v78, v78, v236
	v_mul_f32_e32 v79, v79, v236
	v_mul_f32_e32 v80, v80, v236
	v_mul_f32_e32 v81, v81, v236
	v_mul_f32_e32 v82, v82, v236
	v_mul_f32_e32 v83, v83, v236
	v_mul_f32_e32 v84, v84, v236
	v_mul_f32_e32 v85, v85, v236
	v_mul_f32_e32 v86, v86, v236
	v_mul_f32_e32 v87, v87, v236
	v_mul_f32_e32 v88, v88, v236
	v_mul_f32_e32 v89, v89, v236
	v_mul_f32_e32 v90, v90, v236
	v_mul_f32_e32 v91, v91, v236
	v_mul_f32_e32 v92, v92, v236
	v_mul_f32_e32 v93, v93, v236
	v_mul_f32_e32 v94, v94, v236
	v_mul_f32_e32 v95, v95, v236
	v_mul_f32_e32 v96, v96, v237
	v_mul_f32_e32 v97, v97, v237
	v_mul_f32_e32 v98, v98, v237
	v_mul_f32_e32 v99, v99, v237
	v_mul_f32_e32 v100, v100, v237
	v_mul_f32_e32 v101, v101, v237
	v_mul_f32_e32 v102, v102, v237
	v_mul_f32_e32 v103, v103, v237
	v_mul_f32_e32 v104, v104, v237
	v_mul_f32_e32 v105, v105, v237
	v_mul_f32_e32 v106, v106, v237
	v_mul_f32_e32 v107, v107, v237
	v_mul_f32_e32 v108, v108, v237
	v_mul_f32_e32 v109, v109, v237
	v_mul_f32_e32 v110, v110, v237
	v_mul_f32_e32 v111, v111, v237
	v_mul_f32_e32 v112, v112, v237
	v_mul_f32_e32 v113, v113, v237
	v_mul_f32_e32 v114, v114, v237
	v_mul_f32_e32 v115, v115, v237
	v_mul_f32_e32 v116, v116, v237
	v_mul_f32_e32 v117, v117, v237
	v_mul_f32_e32 v118, v118, v237
	v_mul_f32_e32 v119, v119, v237
	v_mul_f32_e32 v120, v120, v237
	v_mul_f32_e32 v121, v121, v237
	v_mul_f32_e32 v122, v122, v237
	v_mul_f32_e32 v123, v123, v237
	v_mul_f32_e32 v124, v124, v237
	v_mul_f32_e32 v125, v125, v237
	v_mul_f32_e32 v126, v126, v237
	v_mul_f32_e32 v127, v127, v237
	s_cmp_eq_u32 s30, 0
	s_cbranch_scc1 .Lgm_norelu
; template <int EPI> ...
;     ...
;     if (EPI == EPI_SCALE || EPI == EPI_PLAIN || EPI == EPI_FF1) {
; #pragma unroll
;       for (int i = 0; i < 16; i++) {
;         const int rl = rbase + (i & 3) + 8 * (i >> 2);
;         const int row = m0 + rl;
;         float v0 = acc0[i], v1 = acc1[i];
;         if (EPI != EPI_PLAIN) { float rs = sRs[rl]; v0 *= rs; v1 *= rs; }
;         if (EPI == EPI_FF1) { v0 = fmaxf(v0, 0.f); v1 = fmaxf(v1, 0.f); v0 *= v0; v1 *= v1; }
;         outb[(size_t)row * ldo + c0] = f2bf(v0);
;         outb[(size_t)row * ldo + c1] = f2bf(v1);
;       }
	v_max_f32_e32 v0, 0, v0
	v_mul_f32_e32 v0, v0, v0
	v_max_f32_e32 v1, 0, v1
	v_mul_f32_e32 v1, v1, v1
	v_max_f32_e32 v2, 0, v2
	v_mul_f32_e32 v2, v2, v2
	v_max_f32_e32 v3, 0, v3
	v_mul_f32_e32 v3, v3, v3
	v_max_f32_e32 v4, 0, v4
	v_mul_f32_e32 v4, v4, v4
	v_max_f32_e32 v5, 0, v5
	v_mul_f32_e32 v5, v5, v5
	v_max_f32_e32 v6, 0, v6
	v_mul_f32_e32 v6, v6, v6
	v_max_f32_e32 v7, 0, v7
	v_mul_f32_e32 v7, v7, v7
	v_max_f32_e32 v8, 0, v8
	v_mul_f32_e32 v8, v8, v8
	v_max_f32_e32 v9, 0, v9
	v_mul_f32_e32 v9, v9, v9
	v_max_f32_e32 v10, 0, v10
	v_mul_f32_e32 v10, v10, v10
	v_max_f32_e32 v11, 0, v11
	v_mul_f32_e32 v11, v11, v11
	v_max_f32_e32 v12, 0, v12
	v_mul_f32_e32 v12, v12, v12
	v_max_f32_e32 v13, 0, v13
	v_mul_f32_e32 v13, v13, v13
	v_max_f32_e32 v14, 0, v14
	v_mul_f32_e32 v14, v14, v14
	v_max_f32_e32 v15, 0, v15
	v_mul_f32_e32 v15, v15, v15
	v_max_f32_e32 v16, 0, v16
	v_mul_f32_e32 v16, v16, v16
	v_max_f32_e32 v17, 0, v17
	v_mul_f32_e32 v17, v17, v17
	v_max_f32_e32 v18, 0, v18
	v_mul_f32_e32 v18, v18, v18
	v_max_f32_e32 v19, 0, v19
	v_mul_f32_e32 v19, v19, v19
	v_max_f32_e32 v20, 0, v20
	v_mul_f32_e32 v20, v20, v20
	v_max_f32_e32 v21, 0, v21
	v_mul_f32_e32 v21, v21, v21
	v_max_f32_e32 v22, 0, v22
	v_mul_f32_e32 v22, v22, v22
	v_max_f32_e32 v23, 0, v23
	v_mul_f32_e32 v23, v23, v23
	v_max_f32_e32 v24, 0, v24
	v_mul_f32_e32 v24, v24, v24
	v_max_f32_e32 v25, 0, v25
	v_mul_f32_e32 v25, v25, v25
	v_max_f32_e32 v26, 0, v26
	v_mul_f32_e32 v26, v26, v26
	v_max_f32_e32 v27, 0, v27
	v_mul_f32_e32 v27, v27, v27
	v_max_f32_e32 v28, 0, v28
	v_mul_f32_e32 v28, v28, v28
	v_max_f32_e32 v29, 0, v29
	v_mul_f32_e32 v29, v29, v29
	v_max_f32_e32 v30, 0, v30
	v_mul_f32_e32 v30, v30, v30
	v_max_f32_e32 v31, 0, v31
	v_mul_f32_e32 v31, v31, v31
	v_max_f32_e32 v32, 0, v32
	v_mul_f32_e32 v32, v32, v32
	v_max_f32_e32 v33, 0, v33
	v_mul_f32_e32 v33, v33, v33
	v_max_f32_e32 v34, 0, v34
	v_mul_f32_e32 v34, v34, v34
	v_max_f32_e32 v35, 0, v35
	v_mul_f32_e32 v35, v35, v35
	v_max_f32_e32 v36, 0, v36
	v_mul_f32_e32 v36, v36, v36
	v_max_f32_e32 v37, 0, v37
	v_mul_f32_e32 v37, v37, v37
	v_max_f32_e32 v38, 0, v38
	v_mul_f32_e32 v38, v38, v38
	v_max_f32_e32 v39, 0, v39
	v_mul_f32_e32 v39, v39, v39
	v_max_f32_e32 v40, 0, v40
	v_mul_f32_e32 v40, v40, v40
	v_max_f32_e32 v41, 0, v41
	v_mul_f32_e32 v41, v41, v41
	v_max_f32_e32 v42, 0, v42
	v_mul_f32_e32 v42, v42, v42
	v_max_f32_e32 v43, 0, v43
	v_mul_f32_e32 v43, v43, v43
	v_max_f32_e32 v44, 0, v44
	v_mul_f32_e32 v44, v44, v44
	v_max_f32_e32 v45, 0, v45
	v_mul_f32_e32 v45, v45, v45
	v_max_f32_e32 v46, 0, v46
	v_mul_f32_e32 v46, v46, v46
	v_max_f32_e32 v47, 0, v47
	v_mul_f32_e32 v47, v47, v47
	v_max_f32_e32 v48, 0, v48
	v_mul_f32_e32 v48, v48, v48
	v_max_f32_e32 v49, 0, v49
	v_mul_f32_e32 v49, v49, v49
	v_max_f32_e32 v50, 0, v50
	v_mul_f32_e32 v50, v50, v50
	v_max_f32_e32 v51, 0, v51
	v_mul_f32_e32 v51, v51, v51
	v_max_f32_e32 v52, 0, v52
	v_mul_f32_e32 v52, v52, v52
	v_max_f32_e32 v53, 0, v53
	v_mul_f32_e32 v53, v53, v53
	v_max_f32_e32 v54, 0, v54
	v_mul_f32_e32 v54, v54, v54
	v_max_f32_e32 v55, 0, v55
	v_mul_f32_e32 v55, v55, v55
	v_max_f32_e32 v56, 0, v56
	v_mul_f32_e32 v56, v56, v56
	v_max_f32_e32 v57, 0, v57
	v_mul_f32_e32 v57, v57, v57
	v_max_f32_e32 v58, 0, v58
	v_mul_f32_e32 v58, v58, v58
	v_max_f32_e32 v59, 0, v59
	v_mul_f32_e32 v59, v59, v59
	v_max_f32_e32 v60, 0, v60
	v_mul_f32_e32 v60, v60, v60
	v_max_f32_e32 v61, 0, v61
	v_mul_f32_e32 v61, v61, v61
	v_max_f32_e32 v62, 0, v62
	v_mul_f32_e32 v62, v62, v62
	v_max_f32_e32 v63, 0, v63
	v_mul_f32_e32 v63, v63, v63
	v_max_f32_e32 v64, 0, v64
	v_mul_f32_e32 v64, v64, v64
	v_max_f32_e32 v65, 0, v65
; template <int EPI> ...
;     ...
;     if (EPI == EPI_SCALE || EPI == EPI_PLAIN || EPI == EPI_FF1) {
; #pragma unroll
;       for (int i = 0; i < 16; i++) {
;         const int rl = rbase + (i & 3) + 8 * (i >> 2);
;         const int row = m0 + rl;
;         float v0 = acc0[i], v1 = acc1[i];
;         if (EPI != EPI_PLAIN) { float rs = sRs[rl]; v0 *= rs; v1 *= rs; }
;         if (EPI == EPI_FF1) { v0 = fmaxf(v0, 0.f); v1 = fmaxf(v1, 0.f); v0 *= v0; v1 *= v1; }
;         outb[(size_t)row * ldo + c0] = f2bf(v0);
;         outb[(size_t)row * ldo + c1] = f2bf(v1);
;       }
	v_mul_f32_e32 v65, v65, v65
	v_max_f32_e32 v66, 0, v66
	v_mul_f32_e32 v66, v66, v66
	v_max_f32_e32 v67, 0, v67
	v_mul_f32_e32 v67, v67, v67
	v_max_f32_e32 v68, 0, v68
	v_mul_f32_e32 v68, v68, v68
	v_max_f32_e32 v69, 0, v69
	v_mul_f32_e32 v69, v69, v69
	v_max_f32_e32 v70, 0, v70
	v_mul_f32_e32 v70, v70, v70
	v_max_f32_e32 v71, 0, v71
	v_mul_f32_e32 v71, v71, v71
	v_max_f32_e32 v72, 0, v72
	v_mul_f32_e32 v72, v72, v72
	v_max_f32_e32 v73, 0, v73
	v_mul_f32_e32 v73, v73, v73
	v_max_f32_e32 v74, 0, v74
	v_mul_f32_e32 v74, v74, v74
	v_max_f32_e32 v75, 0, v75
	v_mul_f32_e32 v75, v75, v75
	v_max_f32_e32 v76, 0, v76
	v_mul_f32_e32 v76, v76, v76
	v_max_f32_e32 v77, 0, v77
	v_mul_f32_e32 v77, v77, v77
	v_max_f32_e32 v78, 0, v78
	v_mul_f32_e32 v78, v78, v78
	v_max_f32_e32 v79, 0, v79
	v_mul_f32_e32 v79, v79, v79
	v_max_f32_e32 v80, 0, v80
	v_mul_f32_e32 v80, v80, v80
	v_max_f32_e32 v81, 0, v81
	v_mul_f32_e32 v81, v81, v81
	v_max_f32_e32 v82, 0, v82
	v_mul_f32_e32 v82, v82, v82
	v_max_f32_e32 v83, 0, v83
	v_mul_f32_e32 v83, v83, v83
	v_max_f32_e32 v84, 0, v84
	v_mul_f32_e32 v84, v84, v84
	v_max_f32_e32 v85, 0, v85
	v_mul_f32_e32 v85, v85, v85
	v_max_f32_e32 v86, 0, v86
	v_mul_f32_e32 v86, v86, v86
	v_max_f32_e32 v87, 0, v87
	v_mul_f32_e32 v87, v87, v87
	v_max_f32_e32 v88, 0, v88
	v_mul_f32_e32 v88, v88, v88
	v_max_f32_e32 v89, 0, v89
	v_mul_f32_e32 v89, v89, v89
	v_max_f32_e32 v90, 0, v90
	v_mul_f32_e32 v90, v90, v90
	v_max_f32_e32 v91, 0, v91
	v_mul_f32_e32 v91, v91, v91
	v_max_f32_e32 v92, 0, v92
	v_mul_f32_e32 v92, v92, v92
	v_max_f32_e32 v93, 0, v93
	v_mul_f32_e32 v93, v93, v93
	v_max_f32_e32 v94, 0, v94
	v_mul_f32_e32 v94, v94, v94
	v_max_f32_e32 v95, 0, v95
	v_mul_f32_e32 v95, v95, v95
	v_max_f32_e32 v96, 0, v96
	v_mul_f32_e32 v96, v96, v96
	v_max_f32_e32 v97, 0, v97
	v_mul_f32_e32 v97, v97, v97
	v_max_f32_e32 v98, 0, v98
	v_mul_f32_e32 v98, v98, v98
	v_max_f32_e32 v99, 0, v99
	v_mul_f32_e32 v99, v99, v99
	v_max_f32_e32 v100, 0, v100
	v_mul_f32_e32 v100, v100, v100
	v_max_f32_e32 v101, 0, v101
	v_mul_f32_e32 v101, v101, v101
	v_max_f32_e32 v102, 0, v102
	v_mul_f32_e32 v102, v102, v102
	v_max_f32_e32 v103, 0, v103
	v_mul_f32_e32 v103, v103, v103
	v_max_f32_e32 v104, 0, v104
	v_mul_f32_e32 v104, v104, v104
	v_max_f32_e32 v105, 0, v105
	v_mul_f32_e32 v105, v105, v105
	v_max_f32_e32 v106, 0, v106
	v_mul_f32_e32 v106, v106, v106
	v_max_f32_e32 v107, 0, v107
	v_mul_f32_e32 v107, v107, v107
	v_max_f32_e32 v108, 0, v108
	v_mul_f32_e32 v108, v108, v108
	v_max_f32_e32 v109, 0, v109
	v_mul_f32_e32 v109, v109, v109
	v_max_f32_e32 v110, 0, v110
	v_mul_f32_e32 v110, v110, v110
	v_max_f32_e32 v111, 0, v111
	v_mul_f32_e32 v111, v111, v111
	v_max_f32_e32 v112, 0, v112
	v_mul_f32_e32 v112, v112, v112
	v_max_f32_e32 v113, 0, v113
	v_mul_f32_e32 v113, v113, v113
	v_max_f32_e32 v114, 0, v114
	v_mul_f32_e32 v114, v114, v114
	v_max_f32_e32 v115, 0, v115
	v_mul_f32_e32 v115, v115, v115
	v_max_f32_e32 v116, 0, v116
	v_mul_f32_e32 v116, v116, v116
	v_max_f32_e32 v117, 0, v117
	v_mul_f32_e32 v117, v117, v117
	v_max_f32_e32 v118, 0, v118
	v_mul_f32_e32 v118, v118, v118
	v_max_f32_e32 v119, 0, v119
	v_mul_f32_e32 v119, v119, v119
	v_max_f32_e32 v120, 0, v120
	v_mul_f32_e32 v120, v120, v120
	v_max_f32_e32 v121, 0, v121
	v_mul_f32_e32 v121, v121, v121
	v_max_f32_e32 v122, 0, v122
	v_mul_f32_e32 v122, v122, v122
	v_max_f32_e32 v123, 0, v123
	v_mul_f32_e32 v123, v123, v123
	v_max_f32_e32 v124, 0, v124
	v_mul_f32_e32 v124, v124, v124
	v_max_f32_e32 v125, 0, v125
	v_mul_f32_e32 v125, v125, v125
	v_max_f32_e32 v126, 0, v126
	v_mul_f32_e32 v126, v126, v126
	v_max_f32_e32 v127, 0, v127
	v_mul_f32_e32 v127, v127, v127

; template <int EPI> ...
;     ...
;     } else if (EPI == EPI_RES) {
; #pragma unroll
;       for (int i = 0; i < 16; i++) {
;         const int rl = rbase + (i & 3) + 8 * (i >> 2);
;         const int row = m0 + rl;
;         float v0 = acc0[i], v1 = acc1[i];
;         xf[(size_t)row * 1024 + c0] = v0;
;         xf[(size_t)row * 1024 + c1] = v1;
;         outb[(size_t)row * 1024 + c0] = f2bf(v0);
;         outb[(size_t)row * 1024 + c1] = f2bf(v1);
;         float s = hsum32(v0 * v0 + v1 * v1);
;         if ((lane & 31) == 0) part[(size_t)row * 16 + nt * 2 + wn] = s;
;       }
; template <int EPI>
; __device__ __forceinline__ void gemm_phase(const Params& p, const u16* __restrict__ A, int lda, const u16* __restrict__ BT, int ldb,
;                            int K, int N, u16* __restrict__ outb, int ldo, int resid_in, int boff) {
;     ...
;     if (EPI == EPI_RES && !part_unit) {
;       const int cc0 = n0 + wn * 64 + (lane & 31);
;       float* xfq = p.out;
; #pragma unroll
;       for (int i = 0; i < 16; i++) {
;         const int row = m0 + wm * 64 + 4 * (lane >> 5) + (i & 3) + 8 * (i >> 2);
;         const float* ra = resid_in ? xrow(p, row) : (xfq + (size_t)row * 1024);
;         const float* rb = resid_in ? xrow(p, row + 32) : (xfq + (size_t)(row + 32) * 1024);
;         acc00[i] = ra[cc0]; acc01[i] = ra[cc0 + 32];
;         acc10[i] = rb[cc0]; acc11[i] = rb[cc0 + 32];
;       }
.Lgc_epi_res:
	s_lshl_b32 s11, s6, 8
	s_lshl_b32 s12, s4, 6
	s_add_u32 s11, s11, s12
	v_add_u32_e32 v238, s11, v248
	v_lshlrev_b32_e32 v243, 12, v238
	s_lshl_b32 s11, s7, 7
	v_lshl_add_u32 v239, v249, 2, s11
	v_lshlrev_b32_e32 v239, 2, v239
	v_add_u32_e32 v243, v243, v239
	v_add_u32_e32 v244, 0x10000, v243
	v_add_u32_e32 v245, 0x10000, v244
	v_add_u32_e32 v246, 0x10000, v245
	v_lshlrev_b32_e32 v247, 6, v238
	s_lshl_b32 s11, s7, 3
	v_add_u32_e32 v247, s11, v247
	s_lshl_b32 s11, s6, 8
	s_lshl_b32 s12, s4, 6
	s_add_u32 s11, s11, s12
	v_add_u32_e32 v238, s11, v248
	v_mul_lo_u32 v230, v238, s24
	s_lshl_b32 s11, s7, 7
	s_add_u32 s11, s11, s47
	v_and_b32_e32 v239, 1, v249
	v_lshrrev_b32_e32 v240, 1, v249
	v_lshlrev_b32_e32 v239, 4, v239
	v_lshl_add_u32 v239, v240, 3, v239
	v_add_u32_e32 v239, s11, v239
	v_lshlrev_b32_e32 v239, 1, v239
	v_add_u32_e32 v230, v230, v239
	s_lshl_b32 s11, s24, 4
	v_add_u32_e32 v231, s11, v230
	v_add_u32_e32 v232, s11, v231
	v_add_u32_e32 v233, s11, v232
	global_load_dwordx4 v[130:133], v243, s[48:49]
	global_load_dwordx4 v[134:137], v243, s[48:49] offset:64
	global_load_dwordx4 v[138:141], v243, s[48:49] offset:128
	global_load_dwordx4 v[142:145], v243, s[48:49] offset:192
	global_load_dwordx4 v[146:149], v243, s[48:49] offset:256
	global_load_dwordx4 v[150:153], v243, s[48:49] offset:320
	global_load_dwordx4 v[154:157], v243, s[48:49] offset:384
	global_load_dwordx4 v[158:161], v243, s[48:49] offset:448
	global_load_dwordx4 v[162:165], v244, s[48:49]
	global_load_dwordx4 v[166:169], v244, s[48:49] offset:64
	global_load_dwordx4 v[170:173], v244, s[48:49] offset:128
	global_load_dwordx4 v[174:177], v244, s[48:49] offset:192
	global_load_dwordx4 v[178:181], v244, s[48:49] offset:256
	global_load_dwordx4 v[182:185], v244, s[48:49] offset:320
	global_load_dwordx4 v[186:189], v244, s[48:49] offset:384
	global_load_dwordx4 v[190:193], v244, s[48:49] offset:448
	global_load_dwordx4 v[194:197], v245, s[48:49]
	global_load_dwordx4 v[198:201], v245, s[48:49] offset:64
	global_load_dwordx4 v[202:205], v245, s[48:49] offset:128
	global_load_dwordx4 v[206:209], v245, s[48:49] offset:192
	global_load_dwordx4 v[210:213], v245, s[48:49] offset:256
	global_load_dwordx4 v[214:217], v245, s[48:49] offset:320
	global_load_dwordx4 v[218:221], v245, s[48:49] offset:384
	global_load_dwordx4 v[222:225], v245, s[48:49] offset:448
	s_waitcnt vmcnt(23)
	v_add_f32_e32 v0, v0, v130
	v_add_f32_e32 v1, v1, v131
	v_add_f32_e32 v2, v2, v132
	v_add_f32_e32 v3, v3, v133
	global_load_dwordx4 v[130:133], v246, s[48:49]
	s_waitcnt vmcnt(23)
	v_add_f32_e32 v4, v4, v134
	v_add_f32_e32 v5, v5, v135
	v_add_f32_e32 v6, v6, v136
	v_add_f32_e32 v7, v7, v137
	global_load_dwordx4 v[134:137], v246, s[48:49] offset:64
	s_waitcnt vmcnt(23)
	v_add_f32_e32 v8, v8, v138
	v_add_f32_e32 v9, v9, v139
	v_add_f32_e32 v10, v10, v140
	v_add_f32_e32 v11, v11, v141
	global_load_dwordx4 v[138:141], v246, s[48:49] offset:128
	s_waitcnt vmcnt(23)
	v_add_f32_e32 v12, v12, v142
	v_add_f32_e32 v13, v13, v143
	v_add_f32_e32 v14, v14, v144
	v_add_f32_e32 v15, v15, v145
	global_load_dwordx4 v[142:145], v246, s[48:49] offset:192
	s_waitcnt vmcnt(23)
	v_add_f32_e32 v16, v16, v146
	v_add_f32_e32 v17, v17, v147
	v_add_f32_e32 v18, v18, v148
	v_add_f32_e32 v19, v19, v149
	global_load_dwordx4 v[146:149], v246, s[48:49] offset:256
	s_waitcnt vmcnt(23)
	v_add_f32_e32 v20, v20, v150
	v_add_f32_e32 v21, v21, v151
	v_add_f32_e32 v22, v22, v152
	v_add_f32_e32 v23, v23, v153
	global_load_dwordx4 v[150:153], v246, s[48:49] offset:320
	s_waitcnt vmcnt(23)
	v_add_f32_e32 v24, v24, v154
	v_add_f32_e32 v25, v25, v155
	v_add_f32_e32 v26, v26, v156
	v_add_f32_e32 v27, v27, v157
	global_load_dwordx4 v[154:157], v246, s[48:49] offset:384
	s_waitcnt vmcnt(23)
	v_add_f32_e32 v28, v28, v158
	v_add_f32_e32 v29, v29, v159
	v_add_f32_e32 v30, v30, v160
	v_add_f32_e32 v31, v31, v161
	global_load_dwordx4 v[158:161], v246, s[48:49] offset:448
	s_waitcnt vmcnt(23)
	v_add_f32_e32 v32, v32, v162
	v_add_f32_e32 v33, v33, v163
	v_add_f32_e32 v34, v34, v164
	v_add_f32_e32 v35, v35, v165
	s_waitcnt vmcnt(22)
	v_add_f32_e32 v36, v36, v166
	v_add_f32_e32 v37, v37, v167
	v_add_f32_e32 v38, v38, v168
	v_add_f32_e32 v39, v39, v169
	s_waitcnt vmcnt(21)
	v_add_f32_e32 v40, v40, v170
	v_add_f32_e32 v41, v41, v171
	v_add_f32_e32 v42, v42, v172
	v_add_f32_e32 v43, v43, v173
	s_waitcnt vmcnt(20)
	v_add_f32_e32 v44, v44, v174
	v_add_f32_e32 v45, v45, v175
	v_add_f32_e32 v46, v46, v176
	v_add_f32_e32 v47, v47, v177
	s_waitcnt vmcnt(19)
	v_add_f32_e32 v48, v48, v178
	v_add_f32_e32 v49, v49, v179
	v_add_f32_e32 v50, v50, v180
	v_add_f32_e32 v51, v51, v181
	s_waitcnt vmcnt(18)
	v_add_f32_e32 v52, v52, v182
	v_add_f32_e32 v53, v53, v183
	v_add_f32_e32 v54, v54, v184
	v_add_f32_e32 v55, v55, v185
	s_waitcnt vmcnt(17)
	v_add_f32_e32 v56, v56, v186
	v_add_f32_e32 v57, v57, v187
	v_add_f32_e32 v58, v58, v188
	v_add_f32_e32 v59, v59, v189
	s_waitcnt vmcnt(16)
	v_add_f32_e32 v60, v60, v190
	v_add_f32_e32 v61, v61, v191
	v_add_f32_e32 v62, v62, v192
	v_add_f32_e32 v63, v63, v193
	s_waitcnt vmcnt(15)
	v_add_f32_e32 v64, v64, v194
	v_add_f32_e32 v65, v65, v195
	v_add_f32_e32 v66, v66, v196
	v_add_f32_e32 v67, v67, v197
	s_waitcnt vmcnt(14)
	v_add_f32_e32 v68, v68, v198
	v_add_f32_e32 v69, v69, v199
	v_add_f32_e32 v70, v70, v200
	v_add_f32_e32 v71, v71, v201
	s_waitcnt vmcnt(13)
	v_add_f32_e32 v72, v72, v202
	v_add_f32_e32 v73, v73, v203
	v_add_f32_e32 v74, v74, v204
	v_add_f32_e32 v75, v75, v205
	s_waitcnt vmcnt(12)
	v_add_f32_e32 v76, v76, v206
	v_add_f32_e32 v77, v77, v207
	v_add_f32_e32 v78, v78, v208
	v_add_f32_e32 v79, v79, v209
	s_waitcnt vmcnt(11)
; template <int EPI> ...
;     ...
;       for (int i = 0; i < 16; i++) {
;         const int rl = rbase + (i & 3) + 8 * (i >> 2);
;         const int row = m0 + rl;
;         float v0 = acc0[i], v1 = acc1[i];
;         xf[(size_t)row * 1024 + c0] = v0;
;         xf[(size_t)row * 1024 + c1] = v1;
;         outb[(size_t)row * 1024 + c0] = f2bf(v0);
;         outb[(size_t)row * 1024 + c1] = f2bf(v1);
;         float s = hsum32(v0 * v0 + v1 * v1);
;         if ((lane & 31) == 0) part[(size_t)row * 16 + nt * 2 + wn] = s;
	v_add_f32_e32 v80, v80, v210
	v_add_f32_e32 v81, v81, v211
	v_add_f32_e32 v82, v82, v212
	v_add_f32_e32 v83, v83, v213
	s_waitcnt vmcnt(10)
	v_add_f32_e32 v84, v84, v214
	v_add_f32_e32 v85, v85, v215
	v_add_f32_e32 v86, v86, v216
	v_add_f32_e32 v87, v87, v217
	s_waitcnt vmcnt(9)
	v_add_f32_e32 v88, v88, v218
	v_add_f32_e32 v89, v89, v219
	v_add_f32_e32 v90, v90, v220
	v_add_f32_e32 v91, v91, v221
	s_waitcnt vmcnt(8)
	v_add_f32_e32 v92, v92, v222
	v_add_f32_e32 v93, v93, v223
	v_add_f32_e32 v94, v94, v224
	v_add_f32_e32 v95, v95, v225
	s_waitcnt vmcnt(7)
	v_add_f32_e32 v96, v96, v130
	v_add_f32_e32 v97, v97, v131
	v_add_f32_e32 v98, v98, v132
	v_add_f32_e32 v99, v99, v133
	s_waitcnt vmcnt(6)
	v_add_f32_e32 v100, v100, v134
	v_add_f32_e32 v101, v101, v135
	v_add_f32_e32 v102, v102, v136
	v_add_f32_e32 v103, v103, v137
	s_waitcnt vmcnt(5)
	v_add_f32_e32 v104, v104, v138
	v_add_f32_e32 v105, v105, v139
	v_add_f32_e32 v106, v106, v140
	v_add_f32_e32 v107, v107, v141
	s_waitcnt vmcnt(4)
	v_add_f32_e32 v108, v108, v142
	v_add_f32_e32 v109, v109, v143
	v_add_f32_e32 v110, v110, v144
	v_add_f32_e32 v111, v111, v145
	s_waitcnt vmcnt(3)
	v_add_f32_e32 v112, v112, v146
	v_add_f32_e32 v113, v113, v147
	v_add_f32_e32 v114, v114, v148
	v_add_f32_e32 v115, v115, v149
	s_waitcnt vmcnt(2)
	v_add_f32_e32 v116, v116, v150
	v_add_f32_e32 v117, v117, v151
	v_add_f32_e32 v118, v118, v152
	v_add_f32_e32 v119, v119, v153
	s_waitcnt vmcnt(1)
	v_add_f32_e32 v120, v120, v154
	v_add_f32_e32 v121, v121, v155
	v_add_f32_e32 v122, v122, v156
	v_add_f32_e32 v123, v123, v157
	s_waitcnt vmcnt(0)
	v_add_f32_e32 v124, v124, v158
	v_add_f32_e32 v125, v125, v159
	v_add_f32_e32 v126, v126, v160
	v_add_f32_e32 v127, v127, v161
	global_store_dwordx4 v243, v[0:3], s[94:95]
	v_mul_f32_e32 v234, v0, v0
	v_fmac_f32_e32 v234, v1, v1
	v_fmac_f32_e32 v234, v2, v2
	v_fmac_f32_e32 v234, v3, v3
	global_store_dwordx4 v243, v[4:7], s[94:95] offset:64
	v_fmac_f32_e32 v234, v4, v4
	v_fmac_f32_e32 v234, v5, v5
	v_fmac_f32_e32 v234, v6, v6
	v_fmac_f32_e32 v234, v7, v7
	global_store_dwordx4 v243, v[8:11], s[94:95] offset:128
	v_fmac_f32_e32 v234, v8, v8
	v_fmac_f32_e32 v234, v9, v9
	v_fmac_f32_e32 v234, v10, v10
	v_fmac_f32_e32 v234, v11, v11
	global_store_dwordx4 v243, v[12:15], s[94:95] offset:192
	v_fmac_f32_e32 v234, v12, v12
	v_fmac_f32_e32 v234, v13, v13
	v_fmac_f32_e32 v234, v14, v14
	v_fmac_f32_e32 v234, v15, v15
	global_store_dwordx4 v243, v[16:19], s[94:95] offset:256
	v_fmac_f32_e32 v234, v16, v16
	v_fmac_f32_e32 v234, v17, v17
	v_fmac_f32_e32 v234, v18, v18
	v_fmac_f32_e32 v234, v19, v19
	global_store_dwordx4 v243, v[20:23], s[94:95] offset:320
	v_fmac_f32_e32 v234, v20, v20
	v_fmac_f32_e32 v234, v21, v21
	v_fmac_f32_e32 v234, v22, v22
	v_fmac_f32_e32 v234, v23, v23
	global_store_dwordx4 v243, v[24:27], s[94:95] offset:384
	v_fmac_f32_e32 v234, v24, v24
	v_fmac_f32_e32 v234, v25, v25
	v_fmac_f32_e32 v234, v26, v26
	v_fmac_f32_e32 v234, v27, v27
	global_store_dwordx4 v243, v[28:31], s[94:95] offset:448
	v_fmac_f32_e32 v234, v28, v28
	v_fmac_f32_e32 v234, v29, v29
	v_fmac_f32_e32 v234, v30, v30
	v_fmac_f32_e32 v234, v31, v31
	global_store_dwordx4 v244, v[32:35], s[94:95]
	v_mul_f32_e32 v235, v32, v32
	v_fmac_f32_e32 v235, v33, v33
	v_fmac_f32_e32 v235, v34, v34
	v_fmac_f32_e32 v235, v35, v35
	global_store_dwordx4 v244, v[36:39], s[94:95] offset:64
	v_fmac_f32_e32 v235, v36, v36
	v_fmac_f32_e32 v235, v37, v37
	v_fmac_f32_e32 v235, v38, v38
	v_fmac_f32_e32 v235, v39, v39
	global_store_dwordx4 v244, v[40:43], s[94:95] offset:128
	v_fmac_f32_e32 v235, v40, v40
	v_fmac_f32_e32 v235, v41, v41
	v_fmac_f32_e32 v235, v42, v42
	v_fmac_f32_e32 v235, v43, v43
	global_store_dwordx4 v244, v[44:47], s[94:95] offset:192
	v_fmac_f32_e32 v235, v44, v44
	v_fmac_f32_e32 v235, v45, v45
	v_fmac_f32_e32 v235, v46, v46
	v_fmac_f32_e32 v235, v47, v47
	global_store_dwordx4 v244, v[48:51], s[94:95] offset:256
	v_fmac_f32_e32 v235, v48, v48
	v_fmac_f32_e32 v235, v49, v49
	v_fmac_f32_e32 v235, v50, v50
	v_fmac_f32_e32 v235, v51, v51
	global_store_dwordx4 v244, v[52:55], s[94:95] offset:320
	v_fmac_f32_e32 v235, v52, v52
	v_fmac_f32_e32 v235, v53, v53
	v_fmac_f32_e32 v235, v54, v54
	v_fmac_f32_e32 v235, v55, v55
	global_store_dwordx4 v244, v[56:59], s[94:95] offset:384
	v_fmac_f32_e32 v235, v56, v56
	v_fmac_f32_e32 v235, v57, v57
	v_fmac_f32_e32 v235, v58, v58
	v_fmac_f32_e32 v235, v59, v59
	global_store_dwordx4 v244, v[60:63], s[94:95] offset:448
	v_fmac_f32_e32 v235, v60, v60
	v_fmac_f32_e32 v235, v61, v61
	v_fmac_f32_e32 v235, v62, v62
	v_fmac_f32_e32 v235, v63, v63
	global_store_dwordx4 v245, v[64:67], s[94:95]
	v_mul_f32_e32 v236, v64, v64
	v_fmac_f32_e32 v236, v65, v65
	v_fmac_f32_e32 v236, v66, v66
	v_fmac_f32_e32 v236, v67, v67
	global_store_dwordx4 v245, v[68:71], s[94:95] offset:64
	v_fmac_f32_e32 v236, v68, v68
	v_fmac_f32_e32 v236, v69, v69
	v_fmac_f32_e32 v236, v70, v70
	v_fmac_f32_e32 v236, v71, v71
	global_store_dwordx4 v245, v[72:75], s[94:95] offset:128
	v_fmac_f32_e32 v236, v72, v72
	v_fmac_f32_e32 v236, v73, v73
	v_fmac_f32_e32 v236, v74, v74
	v_fmac_f32_e32 v236, v75, v75
	global_store_dwordx4 v245, v[76:79], s[94:95] offset:192
	v_fmac_f32_e32 v236, v76, v76
	v_fmac_f32_e32 v236, v77, v77
	v_fmac_f32_e32 v236, v78, v78
	v_fmac_f32_e32 v236, v79, v79
	global_store_dwordx4 v245, v[80:83], s[94:95] offset:256
	v_fmac_f32_e32 v236, v80, v80
	v_fmac_f32_e32 v236, v81, v81
	v_fmac_f32_e32 v236, v82, v82
	v_fmac_f32_e32 v236, v83, v83
	global_store_dwordx4 v245, v[84:87], s[94:95] offset:320
	v_fmac_f32_e32 v236, v84, v84
	v_fmac_f32_e32 v236, v85, v85
	v_fmac_f32_e32 v236, v86, v86
; template <int EPI> ...
;     ...
;         xf[(size_t)row * 1024 + c0] = v0;
;         xf[(size_t)row * 1024 + c1] = v1;
;         outb[(size_t)row * 1024 + c0] = f2bf(v0);
;         outb[(size_t)row * 1024 + c1] = f2bf(v1);
;         float s = hsum32(v0 * v0 + v1 * v1);
;         if ((lane & 31) == 0) part[(size_t)row * 16 + nt * 2 + wn] = s;
	v_fmac_f32_e32 v236, v87, v87
	global_store_dwordx4 v245, v[88:91], s[94:95] offset:384
	v_fmac_f32_e32 v236, v88, v88
	v_fmac_f32_e32 v236, v89, v89
	v_fmac_f32_e32 v236, v90, v90
	v_fmac_f32_e32 v236, v91, v91
	global_store_dwordx4 v245, v[92:95], s[94:95] offset:448
	v_fmac_f32_e32 v236, v92, v92
	v_fmac_f32_e32 v236, v93, v93
	v_fmac_f32_e32 v236, v94, v94
	v_fmac_f32_e32 v236, v95, v95
	global_store_dwordx4 v246, v[96:99], s[94:95]
	v_mul_f32_e32 v237, v96, v96
	v_fmac_f32_e32 v237, v97, v97
	v_fmac_f32_e32 v237, v98, v98
	v_fmac_f32_e32 v237, v99, v99
	global_store_dwordx4 v246, v[100:103], s[94:95] offset:64
	v_fmac_f32_e32 v237, v100, v100
	v_fmac_f32_e32 v237, v101, v101
	v_fmac_f32_e32 v237, v102, v102
	v_fmac_f32_e32 v237, v103, v103
	global_store_dwordx4 v246, v[104:107], s[94:95] offset:128
	v_fmac_f32_e32 v237, v104, v104
	v_fmac_f32_e32 v237, v105, v105
	v_fmac_f32_e32 v237, v106, v106
	v_fmac_f32_e32 v237, v107, v107
	global_store_dwordx4 v246, v[108:111], s[94:95] offset:192
	v_fmac_f32_e32 v237, v108, v108
	v_fmac_f32_e32 v237, v109, v109
	v_fmac_f32_e32 v237, v110, v110
	v_fmac_f32_e32 v237, v111, v111
	global_store_dwordx4 v246, v[112:115], s[94:95] offset:256
	v_fmac_f32_e32 v237, v112, v112
	v_fmac_f32_e32 v237, v113, v113
	v_fmac_f32_e32 v237, v114, v114
	v_fmac_f32_e32 v237, v115, v115
	global_store_dwordx4 v246, v[116:119], s[94:95] offset:320
	v_fmac_f32_e32 v237, v116, v116
	v_fmac_f32_e32 v237, v117, v117
	v_fmac_f32_e32 v237, v118, v118
	v_fmac_f32_e32 v237, v119, v119
	global_store_dwordx4 v246, v[120:123], s[94:95] offset:384
	v_fmac_f32_e32 v237, v120, v120
	v_fmac_f32_e32 v237, v121, v121
	v_fmac_f32_e32 v237, v122, v122
	v_fmac_f32_e32 v237, v123, v123
	global_store_dwordx4 v246, v[124:127], s[94:95] offset:448
	v_fmac_f32_e32 v237, v124, v124
	v_fmac_f32_e32 v237, v125, v125
	v_fmac_f32_e32 v237, v126, v126
	v_fmac_f32_e32 v237, v127, v127
	s_cmp_eq_u32 s101, 19
	s_cbranch_scc1 .Lgc_res_nobf
	v_cvt_pk_bf16_f32 v0, v0, v1
	v_cvt_pk_bf16_f32 v1, v2, v3
	v_cvt_pk_bf16_f32 v2, v4, v5
	v_cvt_pk_bf16_f32 v3, v6, v7
	s_nop 1
	v_permlane16_swap_b32_e32 v0, v2
	v_permlane16_swap_b32_e32 v1, v3
	global_store_dwordx4 v230, v[0:3], s[22:23]
	v_cvt_pk_bf16_f32 v8, v8, v9
	v_cvt_pk_bf16_f32 v9, v10, v11
	v_cvt_pk_bf16_f32 v10, v12, v13
	v_cvt_pk_bf16_f32 v11, v14, v15
	s_nop 1
	v_permlane16_swap_b32_e32 v8, v10
	v_permlane16_swap_b32_e32 v9, v11
	global_store_dwordx4 v230, v[8:11], s[22:23] offset:64
	v_cvt_pk_bf16_f32 v16, v16, v17
	v_cvt_pk_bf16_f32 v17, v18, v19
	v_cvt_pk_bf16_f32 v18, v20, v21
	v_cvt_pk_bf16_f32 v19, v22, v23
	s_nop 1
	v_permlane16_swap_b32_e32 v16, v18
	v_permlane16_swap_b32_e32 v17, v19
	global_store_dwordx4 v230, v[16:19], s[22:23] offset:128
	v_cvt_pk_bf16_f32 v24, v24, v25
	v_cvt_pk_bf16_f32 v25, v26, v27
	v_cvt_pk_bf16_f32 v26, v28, v29
	v_cvt_pk_bf16_f32 v27, v30, v31
	s_nop 1
	v_permlane16_swap_b32_e32 v24, v26
	v_permlane16_swap_b32_e32 v25, v27
	global_store_dwordx4 v230, v[24:27], s[22:23] offset:192
	v_cvt_pk_bf16_f32 v32, v32, v33
	v_cvt_pk_bf16_f32 v33, v34, v35
	v_cvt_pk_bf16_f32 v34, v36, v37
	v_cvt_pk_bf16_f32 v35, v38, v39
	s_nop 1
	v_permlane16_swap_b32_e32 v32, v34
	v_permlane16_swap_b32_e32 v33, v35
	global_store_dwordx4 v231, v[32:35], s[22:23]
	v_cvt_pk_bf16_f32 v40, v40, v41
	v_cvt_pk_bf16_f32 v41, v42, v43
	v_cvt_pk_bf16_f32 v42, v44, v45
	v_cvt_pk_bf16_f32 v43, v46, v47
	s_nop 1
	v_permlane16_swap_b32_e32 v40, v42
	v_permlane16_swap_b32_e32 v41, v43
	global_store_dwordx4 v231, v[40:43], s[22:23] offset:64
	v_cvt_pk_bf16_f32 v48, v48, v49
	v_cvt_pk_bf16_f32 v49, v50, v51
	v_cvt_pk_bf16_f32 v50, v52, v53
	v_cvt_pk_bf16_f32 v51, v54, v55
	s_nop 1
	v_permlane16_swap_b32_e32 v48, v50
	v_permlane16_swap_b32_e32 v49, v51
	global_store_dwordx4 v231, v[48:51], s[22:23] offset:128
	v_cvt_pk_bf16_f32 v56, v56, v57
	v_cvt_pk_bf16_f32 v57, v58, v59
	v_cvt_pk_bf16_f32 v58, v60, v61
	v_cvt_pk_bf16_f32 v59, v62, v63
	s_nop 1
	v_permlane16_swap_b32_e32 v56, v58
	v_permlane16_swap_b32_e32 v57, v59
	global_store_dwordx4 v231, v[56:59], s[22:23] offset:192
	v_cvt_pk_bf16_f32 v64, v64, v65
	v_cvt_pk_bf16_f32 v65, v66, v67
	v_cvt_pk_bf16_f32 v66, v68, v69
	v_cvt_pk_bf16_f32 v67, v70, v71
	s_nop 1
	v_permlane16_swap_b32_e32 v64, v66
	v_permlane16_swap_b32_e32 v65, v67
	global_store_dwordx4 v232, v[64:67], s[22:23]
	v_cvt_pk_bf16_f32 v72, v72, v73
	v_cvt_pk_bf16_f32 v73, v74, v75
	v_cvt_pk_bf16_f32 v74, v76, v77
	v_cvt_pk_bf16_f32 v75, v78, v79
	s_nop 1
	v_permlane16_swap_b32_e32 v72, v74
	v_permlane16_swap_b32_e32 v73, v75
	global_store_dwordx4 v232, v[72:75], s[22:23] offset:64
	v_cvt_pk_bf16_f32 v80, v80, v81
	v_cvt_pk_bf16_f32 v81, v82, v83
	v_cvt_pk_bf16_f32 v82, v84, v85
	v_cvt_pk_bf16_f32 v83, v86, v87
	s_nop 1
	v_permlane16_swap_b32_e32 v80, v82
	v_permlane16_swap_b32_e32 v81, v83
	global_store_dwordx4 v232, v[80:83], s[22:23] offset:128
	v_cvt_pk_bf16_f32 v88, v88, v89
	v_cvt_pk_bf16_f32 v89, v90, v91
	v_cvt_pk_bf16_f32 v90, v92, v93
	v_cvt_pk_bf16_f32 v91, v94, v95
	s_nop 1
	v_permlane16_swap_b32_e32 v88, v90
	v_permlane16_swap_b32_e32 v89, v91
	global_store_dwordx4 v232, v[88:91], s[22:23] offset:192
	v_cvt_pk_bf16_f32 v96, v96, v97
	v_cvt_pk_bf16_f32 v97, v98, v99
	v_cvt_pk_bf16_f32 v98, v100, v101
	v_cvt_pk_bf16_f32 v99, v102, v103
	s_nop 1
	v_permlane16_swap_b32_e32 v96, v98
	v_permlane16_swap_b32_e32 v97, v99
	global_store_dwordx4 v233, v[96:99], s[22:23]
	v_cvt_pk_bf16_f32 v104, v104, v105
	v_cvt_pk_bf16_f32 v105, v106, v107
	v_cvt_pk_bf16_f32 v106, v108, v109
	v_cvt_pk_bf16_f32 v107, v110, v111
	s_nop 1
	v_permlane16_swap_b32_e32 v104, v106
	v_permlane16_swap_b32_e32 v105, v107
	global_store_dwordx4 v233, v[104:107], s[22:23] offset:64
	v_cvt_pk_bf16_f32 v112, v112, v113
	v_cvt_pk_bf16_f32 v113, v114, v115
	v_cvt_pk_bf16_f32 v114, v116, v117
	v_cvt_pk_bf16_f32 v115, v118, v119
	s_nop 1
	v_permlane16_swap_b32_e32 v112, v114
	v_permlane16_swap_b32_e32 v113, v115
	global_store_dwordx4 v233, v[112:115], s[22:23] offset:128
	v_cvt_pk_bf16_f32 v120, v120, v121
	v_cvt_pk_bf16_f32 v121, v122, v123
	v_cvt_pk_bf16_f32 v122, v124, v125
	v_cvt_pk_bf16_f32 v123, v126, v127
	s_nop 1
	v_permlane16_swap_b32_e32 v120, v122
	v_permlane16_swap_b32_e32 v121, v123
	global_store_dwordx4 v233, v[120:123], s[22:23] offset:192

; template <int EPI>
; __device__ __forceinline__ void gemm_phase(const Params& p, const u16* __restrict__ A, int lda, const u16* __restrict__ BT, int ldb,
;                            int K, int N, u16* __restrict__ outb, int ldo, int resid_in, int boff) {
;     ...
;     if (EPI == EPI_RES && part_unit) {
;       float* xfp = p.out;
; #pragma unroll
;       for (int i = 0; i < 16; i++) {
;         const int rl = wm * 64 + 4 * (lane >> 5) + (i & 3) + 8 * (i >> 2);
;         float* r0p = xfp + (size_t)(m0 + rl) * 1024;
;         float* r1p = r0p + (size_t)32 * 1024;
;         atomicAdd(r0p + c0, acc00[i]); atomicAdd(r0p + c1, acc01[i]);
;         atomicAdd(r1p + c0, acc10[i]); atomicAdd(r1p + c1, acc11[i]);
;       }
.Lgc_tailN:
	v_mfma_f32_16x16x32_bf16 v[0:3], v[178:181], v[194:197], v[0:3]
	v_mfma_f32_16x16x32_bf16 v[4:7], v[178:181], v[198:201], v[4:7]
	v_mfma_f32_16x16x32_bf16 v[8:11], v[178:181], v[202:205], v[8:11]
	v_mfma_f32_16x16x32_bf16 v[12:15], v[178:181], v[206:209], v[12:15]
	v_mfma_f32_16x16x32_bf16 v[16:19], v[178:181], v[210:213], v[16:19]
	v_mfma_f32_16x16x32_bf16 v[20:23], v[178:181], v[214:217], v[20:23]
	v_mfma_f32_16x16x32_bf16 v[24:27], v[178:181], v[218:221], v[24:27]
	v_mfma_f32_16x16x32_bf16 v[28:31], v[178:181], v[222:225], v[28:31]
	v_mfma_f32_16x16x32_bf16 v[32:35], v[182:185], v[194:197], v[32:35]
	v_mfma_f32_16x16x32_bf16 v[36:39], v[182:185], v[198:201], v[36:39]
	v_mfma_f32_16x16x32_bf16 v[40:43], v[182:185], v[202:205], v[40:43]
	v_mfma_f32_16x16x32_bf16 v[44:47], v[182:185], v[206:209], v[44:47]
	v_mfma_f32_16x16x32_bf16 v[48:51], v[182:185], v[210:213], v[48:51]
	v_mfma_f32_16x16x32_bf16 v[52:55], v[182:185], v[214:217], v[52:55]
	v_mfma_f32_16x16x32_bf16 v[56:59], v[182:185], v[218:221], v[56:59]
	v_mfma_f32_16x16x32_bf16 v[60:63], v[182:185], v[222:225], v[60:63]
	v_mfma_f32_16x16x32_bf16 v[64:67], v[186:189], v[194:197], v[64:67]
	v_mfma_f32_16x16x32_bf16 v[68:71], v[186:189], v[198:201], v[68:71]
	v_mfma_f32_16x16x32_bf16 v[72:75], v[186:189], v[202:205], v[72:75]
	v_mfma_f32_16x16x32_bf16 v[76:79], v[186:189], v[206:209], v[76:79]
	v_mfma_f32_16x16x32_bf16 v[80:83], v[186:189], v[210:213], v[80:83]
	v_mfma_f32_16x16x32_bf16 v[84:87], v[186:189], v[214:217], v[84:87]
	v_mfma_f32_16x16x32_bf16 v[88:91], v[186:189], v[218:221], v[88:91]
	v_mfma_f32_16x16x32_bf16 v[92:95], v[186:189], v[222:225], v[92:95]
	v_mfma_f32_16x16x32_bf16 v[96:99], v[190:193], v[194:197], v[96:99]
	v_mfma_f32_16x16x32_bf16 v[100:103], v[190:193], v[198:201], v[100:103]
	v_mfma_f32_16x16x32_bf16 v[104:107], v[190:193], v[202:205], v[104:107]
	v_mfma_f32_16x16x32_bf16 v[108:111], v[190:193], v[206:209], v[108:111]
	v_mfma_f32_16x16x32_bf16 v[112:115], v[190:193], v[210:213], v[112:115]
	v_mfma_f32_16x16x32_bf16 v[116:119], v[190:193], v[214:217], v[116:119]
	v_mfma_f32_16x16x32_bf16 v[120:123], v[190:193], v[218:221], v[120:123]
	v_mfma_f32_16x16x32_bf16 v[124:127], v[190:193], v[222:225], v[124:127]
	s_lshl_b32 s11, s6, 8
	s_lshl_b32 s12, s4, 6
	s_add_u32 s11, s11, s12
	v_add_u32_e32 v238, s11, v248
	v_sub_u32_e32 v238, v238, v248
	v_lshl_add_u32 v238, v249, 2, v238
	v_lshlrev_b32_e32 v243, 12, v238
	s_lshl_b32 s11, s7, 7
	v_add_u32_e32 v239, s11, v248
	v_lshlrev_b32_e32 v239, 2, v239
	v_add_u32_e32 v243, v243, v239
	s_nop 7
	s_mov_b32 s36, s94
	s_mov_b32 s37, s95
	global_atomic_add_f32 v243, v0, s[36:37]
	global_atomic_add_f32 v243, v4, s[36:37] offset:64
	global_atomic_add_f32 v243, v8, s[36:37] offset:128
	global_atomic_add_f32 v243, v12, s[36:37] offset:192
	global_atomic_add_f32 v243, v16, s[36:37] offset:256
	global_atomic_add_f32 v243, v20, s[36:37] offset:320
	global_atomic_add_f32 v243, v24, s[36:37] offset:384
	global_atomic_add_f32 v243, v28, s[36:37] offset:448
	s_add_u32 s36, s36, 0x1000
	s_addc_u32 s37, s37, 0
	global_atomic_add_f32 v243, v1, s[36:37]
	global_atomic_add_f32 v243, v5, s[36:37] offset:64
	global_atomic_add_f32 v243, v9, s[36:37] offset:128
	global_atomic_add_f32 v243, v13, s[36:37] offset:192
	global_atomic_add_f32 v243, v17, s[36:37] offset:256
	global_atomic_add_f32 v243, v21, s[36:37] offset:320
	global_atomic_add_f32 v243, v25, s[36:37] offset:384
	global_atomic_add_f32 v243, v29, s[36:37] offset:448
	s_add_u32 s36, s36, 0x1000
	s_addc_u32 s37, s37, 0
	global_atomic_add_f32 v243, v2, s[36:37]
	global_atomic_add_f32 v243, v6, s[36:37] offset:64
	global_atomic_add_f32 v243, v10, s[36:37] offset:128
	global_atomic_add_f32 v243, v14, s[36:37] offset:192
	global_atomic_add_f32 v243, v18, s[36:37] offset:256
	global_atomic_add_f32 v243, v22, s[36:37] offset:320
	global_atomic_add_f32 v243, v26, s[36:37] offset:384
	global_atomic_add_f32 v243, v30, s[36:37] offset:448
	s_add_u32 s36, s36, 0x1000
	s_addc_u32 s37, s37, 0
	global_atomic_add_f32 v243, v3, s[36:37]
	global_atomic_add_f32 v243, v7, s[36:37] offset:64
	global_atomic_add_f32 v243, v11, s[36:37] offset:128
	global_atomic_add_f32 v243, v15, s[36:37] offset:192
	global_atomic_add_f32 v243, v19, s[36:37] offset:256
	global_atomic_add_f32 v243, v23, s[36:37] offset:320
	global_atomic_add_f32 v243, v27, s[36:37] offset:384
	global_atomic_add_f32 v243, v31, s[36:37] offset:448
	s_add_u32 s36, s36, 0xd000
	s_addc_u32 s37, s37, 0
	global_atomic_add_f32 v243, v32, s[36:37]
	global_atomic_add_f32 v243, v36, s[36:37] offset:64
	global_atomic_add_f32 v243, v40, s[36:37] offset:128
	global_atomic_add_f32 v243, v44, s[36:37] offset:192
	global_atomic_add_f32 v243, v48, s[36:37] offset:256
	global_atomic_add_f32 v243, v52, s[36:37] offset:320
	global_atomic_add_f32 v243, v56, s[36:37] offset:384
	global_atomic_add_f32 v243, v60, s[36:37] offset:448
	s_add_u32 s36, s36, 0x1000
	s_addc_u32 s37, s37, 0
	global_atomic_add_f32 v243, v33, s[36:37]
	global_atomic_add_f32 v243, v37, s[36:37] offset:64
	global_atomic_add_f32 v243, v41, s[36:37] offset:128
	global_atomic_add_f32 v243, v45, s[36:37] offset:192
	global_atomic_add_f32 v243, v49, s[36:37] offset:256
	global_atomic_add_f32 v243, v53, s[36:37] offset:320
	global_atomic_add_f32 v243, v57, s[36:37] offset:384
	global_atomic_add_f32 v243, v61, s[36:37] offset:448
	s_add_u32 s36, s36, 0x1000
	s_addc_u32 s37, s37, 0
	global_atomic_add_f32 v243, v34, s[36:37]
	global_atomic_add_f32 v243, v38, s[36:37] offset:64
	global_atomic_add_f32 v243, v42, s[36:37] offset:128
	global_atomic_add_f32 v243, v46, s[36:37] offset:192
; template <int EPI>
; __device__ __forceinline__ void gemm_phase(const Params& p, const u16* __restrict__ A, int lda, const u16* __restrict__ BT, int ldb,
;                            int K, int N, u16* __restrict__ outb, int ldo, int resid_in, int boff) {
;     ...
;       for (int i = 0; i < 16; i++) {
;         const int rl = wm * 64 + 4 * (lane >> 5) + (i & 3) + 8 * (i >> 2);
;         float* r0p = xfp + (size_t)(m0 + rl) * 1024;
;         float* r1p = r0p + (size_t)32 * 1024;
;         atomicAdd(r0p + c0, acc00[i]); atomicAdd(r0p + c1, acc01[i]);
;         atomicAdd(r1p + c0, acc10[i]); atomicAdd(r1p + c1, acc11[i]);
;       }
	global_atomic_add_f32 v243, v50, s[36:37] offset:256
	global_atomic_add_f32 v243, v54, s[36:37] offset:320
	global_atomic_add_f32 v243, v58, s[36:37] offset:384
	global_atomic_add_f32 v243, v62, s[36:37] offset:448
	s_add_u32 s36, s36, 0x1000
	s_addc_u32 s37, s37, 0
	global_atomic_add_f32 v243, v35, s[36:37]
	global_atomic_add_f32 v243, v39, s[36:37] offset:64
	global_atomic_add_f32 v243, v43, s[36:37] offset:128
	global_atomic_add_f32 v243, v47, s[36:37] offset:192
	global_atomic_add_f32 v243, v51, s[36:37] offset:256
	global_atomic_add_f32 v243, v55, s[36:37] offset:320
	global_atomic_add_f32 v243, v59, s[36:37] offset:384
	global_atomic_add_f32 v243, v63, s[36:37] offset:448
	s_add_u32 s36, s36, 0xd000
	s_addc_u32 s37, s37, 0
	global_atomic_add_f32 v243, v64, s[36:37]
	global_atomic_add_f32 v243, v68, s[36:37] offset:64
	global_atomic_add_f32 v243, v72, s[36:37] offset:128
	global_atomic_add_f32 v243, v76, s[36:37] offset:192
	global_atomic_add_f32 v243, v80, s[36:37] offset:256
	global_atomic_add_f32 v243, v84, s[36:37] offset:320
	global_atomic_add_f32 v243, v88, s[36:37] offset:384
	global_atomic_add_f32 v243, v92, s[36:37] offset:448
	s_add_u32 s36, s36, 0x1000
	s_addc_u32 s37, s37, 0
	global_atomic_add_f32 v243, v65, s[36:37]
	global_atomic_add_f32 v243, v69, s[36:37] offset:64
	global_atomic_add_f32 v243, v73, s[36:37] offset:128
	global_atomic_add_f32 v243, v77, s[36:37] offset:192
	global_atomic_add_f32 v243, v81, s[36:37] offset:256
	global_atomic_add_f32 v243, v85, s[36:37] offset:320
	global_atomic_add_f32 v243, v89, s[36:37] offset:384
	global_atomic_add_f32 v243, v93, s[36:37] offset:448
	s_add_u32 s36, s36, 0x1000
	s_addc_u32 s37, s37, 0
	global_atomic_add_f32 v243, v66, s[36:37]
	global_atomic_add_f32 v243, v70, s[36:37] offset:64
	global_atomic_add_f32 v243, v74, s[36:37] offset:128
	global_atomic_add_f32 v243, v78, s[36:37] offset:192
	global_atomic_add_f32 v243, v82, s[36:37] offset:256
	global_atomic_add_f32 v243, v86, s[36:37] offset:320
	global_atomic_add_f32 v243, v90, s[36:37] offset:384
	global_atomic_add_f32 v243, v94, s[36:37] offset:448
	s_add_u32 s36, s36, 0x1000
	s_addc_u32 s37, s37, 0
	global_atomic_add_f32 v243, v67, s[36:37]
	global_atomic_add_f32 v243, v71, s[36:37] offset:64
	global_atomic_add_f32 v243, v75, s[36:37] offset:128
	global_atomic_add_f32 v243, v79, s[36:37] offset:192
	global_atomic_add_f32 v243, v83, s[36:37] offset:256
	global_atomic_add_f32 v243, v87, s[36:37] offset:320
	global_atomic_add_f32 v243, v91, s[36:37] offset:384
	global_atomic_add_f32 v243, v95, s[36:37] offset:448
	s_add_u32 s36, s36, 0xd000
	s_addc_u32 s37, s37, 0
	global_atomic_add_f32 v243, v96, s[36:37]
	global_atomic_add_f32 v243, v100, s[36:37] offset:64
	global_atomic_add_f32 v243, v104, s[36:37] offset:128
	global_atomic_add_f32 v243, v108, s[36:37] offset:192
	global_atomic_add_f32 v243, v112, s[36:37] offset:256
	global_atomic_add_f32 v243, v116, s[36:37] offset:320
	global_atomic_add_f32 v243, v120, s[36:37] offset:384
	global_atomic_add_f32 v243, v124, s[36:37] offset:448
	s_add_u32 s36, s36, 0x1000
	s_addc_u32 s37, s37, 0
	global_atomic_add_f32 v243, v97, s[36:37]
	global_atomic_add_f32 v243, v101, s[36:37] offset:64
	global_atomic_add_f32 v243, v105, s[36:37] offset:128
	global_atomic_add_f32 v243, v109, s[36:37] offset:192
	global_atomic_add_f32 v243, v113, s[36:37] offset:256
	global_atomic_add_f32 v243, v117, s[36:37] offset:320
	global_atomic_add_f32 v243, v121, s[36:37] offset:384
	global_atomic_add_f32 v243, v125, s[36:37] offset:448
	s_add_u32 s36, s36, 0x1000
	s_addc_u32 s37, s37, 0
	global_atomic_add_f32 v243, v98, s[36:37]
	global_atomic_add_f32 v243, v102, s[36:37] offset:64
	global_atomic_add_f32 v243, v106, s[36:37] offset:128
	global_atomic_add_f32 v243, v110, s[36:37] offset:192
	global_atomic_add_f32 v243, v114, s[36:37] offset:256
	global_atomic_add_f32 v243, v118, s[36:37] offset:320
	global_atomic_add_f32 v243, v122, s[36:37] offset:384
	global_atomic_add_f32 v243, v126, s[36:37] offset:448
	s_add_u32 s36, s36, 0x1000
	s_addc_u32 s37, s37, 0
	global_atomic_add_f32 v243, v99, s[36:37]
	global_atomic_add_f32 v243, v103, s[36:37] offset:64
	global_atomic_add_f32 v243, v107, s[36:37] offset:128
	global_atomic_add_f32 v243, v111, s[36:37] offset:192
	global_atomic_add_f32 v243, v115, s[36:37] offset:256
	global_atomic_add_f32 v243, v119, s[36:37] offset:320
	global_atomic_add_f32 v243, v123, s[36:37] offset:384
	global_atomic_add_f32 v243, v127, s[36:37] offset:448
	s_nop 3
	s_branch .Lgc_next
.Lgc_unitW:
	ds_read_b128 v[130:133], v226
	ds_read_b128 v[146:149], v228
	ds_read_b128 v[150:153], v228 offset:2048
	ds_read_b128 v[134:137], v226 offset:2048
	ds_read_b128 v[138:141], v226 offset:4096
	ds_read_b128 v[142:145], v226 offset:6144
	s_waitcnt lgkmcnt(3)
	v_mfma_f32_16x16x32_bf16 v[0:3], v[146:149], v[130:133], 0
	ds_read_b128 v[178:181], v227
	v_mfma_f32_16x16x32_bf16 v[4:7], v[150:153], v[130:133], 0
	ds_read_b128 v[194:197], v229
	s_waitcnt lgkmcnt(4)
	v_mfma_f32_16x16x32_bf16 v[32:35], v[146:149], v[134:137], 0
	ds_read_b128 v[198:201], v229 offset:2048
	v_mfma_f32_16x16x32_bf16 v[36:39], v[150:153], v[134:137], 0
	ds_read_b128 v[182:185], v227 offset:2048
	s_waitcnt lgkmcnt(5)
	v_mfma_f32_16x16x32_bf16 v[64:67], v[146:149], v[138:141], 0
	ds_read_b128 v[186:189], v227 offset:4096
	v_mfma_f32_16x16x32_bf16 v[68:71], v[150:153], v[138:141], 0
	ds_read_b128 v[190:193], v227 offset:6144
	s_waitcnt lgkmcnt(6)
	v_mfma_f32_16x16x32_bf16 v[96:99], v[146:149], v[142:145], 0
	v_add_u32_e32 v226, s31, v226
	v_add_u32_e32 v227, s31, v227
	v_mfma_f32_16x16x32_bf16 v[100:103], v[150:153], v[142:145], 0
	v_add_u32_e32 v228, s31, v228
	v_add_u32_e32 v229, s31, v229
	s_add_u32 s13, s13, 1
	s_cmp_eq_u32 s13, 3
	s_cselect_b32 s13, 0, s13
	s_cmp_eq_u32 s13, 2
	s_cselect_b32 s31, s34, s35
	s_waitcnt lgkmcnt(0)
	s_barrier
	s_cmp_eq_u32 s18, 0
	s_cbranch_scc1 .Lgc_tailW
; #define RAW_BARRIER() do { asm volatile("s_waitcnt lgkmcnt(0)" ::: "memory"); __builtin_amdgcn_s_barrier(); asm volatile("" ::: "memory"); } while (0)
; template <int EPI>
; __device__ __forceinline__ void gemm_phase(const Params& p, const u16* __restrict__ A, int lda, const u16* __restrict__ BT, int ldb,
;                            int K, int N, u16* __restrict__ outb, int ldo, int resid_in, int boff) {
;     ...
;     for (int kt = 0; kt < KT; kt += 2) {
;       if (kt + 1 < KT) WRITEY(1);
;       if (kt + 3 < KT) LOADY(kt + 3);
;       COMPUTE(0);
;       RAW_BARRIER();
;       if (kt + 1 >= KT) break;
;       if (kt + 2 < KT) WRITEX(0);
;       if (kt + 4 < KT) LOADX(kt + 4);
;       COMPUTE(1);
;       RAW_BARRIER();
;     }
.Lgc_loopW:
	v_mfma_f32_16x16x32_bf16 v[0:3], v[194:197], v[178:181], v[0:3]
	ds_read_b128 v[130:133], v226
	v_mfma_f32_16x16x32_bf16 v[4:7], v[198:201], v[178:181], v[4:7]
	ds_read_b128 v[146:149], v228
	v_mfma_f32_16x16x32_bf16 v[32:35], v[194:197], v[182:185], v[32:35]
	ds_read_b128 v[150:153], v228 offset:2048
	v_mfma_f32_16x16x32_bf16 v[36:39], v[198:201], v[182:185], v[36:39]
	ds_read_b128 v[134:137], v226 offset:2048
	v_mfma_f32_16x16x32_bf16 v[64:67], v[194:197], v[186:189], v[64:67]
	ds_read_b128 v[138:141], v226 offset:4096
	v_mfma_f32_16x16x32_bf16 v[68:71], v[198:201], v[186:189], v[68:71]
	ds_read_b128 v[142:145], v226 offset:6144
	v_mfma_f32_16x16x32_bf16 v[96:99], v[194:197], v[190:193], v[96:99]
	v_mfma_f32_16x16x32_bf16 v[100:103], v[198:201], v[190:193], v[100:103]
	s_waitcnt lgkmcnt(0)
	s_nop 0
	v_mfma_f32_16x16x32_bf16 v[0:3], v[146:149], v[130:133], v[0:3]
	ds_read_b128 v[178:181], v227
	v_mfma_f32_16x16x32_bf16 v[4:7], v[150:153], v[130:133], v[4:7]
	ds_read_b128 v[194:197], v229
	v_mfma_f32_16x16x32_bf16 v[32:35], v[146:149], v[134:137], v[32:35]
	ds_read_b128 v[198:201], v229 offset:2048
	v_mfma_f32_16x16x32_bf16 v[36:39], v[150:153], v[134:137], v[36:39]
	ds_read_b128 v[182:185], v227 offset:2048
	v_mfma_f32_16x16x32_bf16 v[64:67], v[146:149], v[138:141], v[64:67]
	ds_read_b128 v[186:189], v227 offset:4096
	v_mfma_f32_16x16x32_bf16 v[68:71], v[150:153], v[138:141], v[68:71]
	ds_read_b128 v[190:193], v227 offset:6144
	v_mfma_f32_16x16x32_bf16 v[96:99], v[146:149], v[142:145], v[96:99]
	v_add_u32_e32 v226, s31, v226
	v_add_u32_e32 v227, s31, v227
	v_mfma_f32_16x16x32_bf16 v[100:103], v[150:153], v[142:145], v[100:103]
	v_add_u32_e32 v228, s31, v228
	v_add_u32_e32 v229, s31, v229
	s_add_u32 s13, s13, 1
	s_cmp_eq_u32 s13, 3
	s_cselect_b32 s13, 0, s13
	s_cmp_eq_u32 s13, 2
	s_cselect_b32 s31, s34, s35
	s_waitcnt lgkmcnt(0)
	s_barrier
	s_sub_u32 s18, s18, 1
	s_cmp_lg_u32 s18, 0
	s_cbranch_scc1 .Lgc_loopW
; template <int EPI> ...
;     ...
;     if (EPI == EPI_SCALE || EPI == EPI_PLAIN || EPI == EPI_FF1) {
; #pragma unroll
;       for (int i = 0; i < 16; i++) {
;         const int rl = rbase + (i & 3) + 8 * (i >> 2);
;         const int row = m0 + rl;
;         float v0 = acc0[i], v1 = acc1[i];
;         if (EPI != EPI_PLAIN) { float rs = sRs[rl]; v0 *= rs; v1 *= rs; }
;         if (EPI == EPI_FF1) { v0 = fmaxf(v0, 0.f); v1 = fmaxf(v1, 0.f); v0 *= v0; v1 *= v1; }
;         outb[(size_t)row * ldo + c0] = f2bf(v0);
;         outb[(size_t)row * ldo + c1] = f2bf(v1);
;       }
; template <int EPI>
; __device__ __forceinline__ void gemm_phase(const Params& p, const u16* __restrict__ A, int lda, const u16* __restrict__ BT, int ldb,
;                            int K, int N, u16* __restrict__ outb, int ldo, int resid_in, int boff) {
;     ...
;     if (EPI == EPI_SCALE || EPI == EPI_FF1) {
;       if (tid < 256) {
;         const float sq = (pq0.x + pq0.y + pq0.z + pq0.w) + (pq1.x + pq1.y + pq1.z + pq1.w) + (pq2.x + pq2.y + pq2.z + pq2.w) + (pq3.x + pq3.y + pq3.z + pq3.w);
;         sRs[tid] = rsqrtf(sq * (1.0f / 1024.0f) + 1e-6f);
;       }
;       __syncthreads();
;     }
;     const int c0 = n0 + wn * 64 + (lane & 31);
;     const int c1 = c0 + 32;
.Lgc_tailW:
	v_mfma_f32_16x16x32_bf16 v[0:3], v[194:197], v[178:181], v[0:3]
	v_mfma_f32_16x16x32_bf16 v[4:7], v[198:201], v[178:181], v[4:7]
	v_mfma_f32_16x16x32_bf16 v[32:35], v[194:197], v[182:185], v[32:35]
	v_mfma_f32_16x16x32_bf16 v[36:39], v[198:201], v[182:185], v[36:39]
	v_mfma_f32_16x16x32_bf16 v[64:67], v[194:197], v[186:189], v[64:67]
	v_mfma_f32_16x16x32_bf16 v[68:71], v[198:201], v[186:189], v[68:71]
	v_mfma_f32_16x16x32_bf16 v[96:99], v[194:197], v[190:193], v[96:99]
	v_mfma_f32_16x16x32_bf16 v[100:103], v[198:201], v[190:193], v[100:103]
	s_lshl_b32 s11, s6, 8
	s_lshl_b32 s12, s4, 6
	s_add_u32 s11, s11, s12
	v_add_u32_e32 v238, s11, v248
	v_mul_lo_u32 v230, v238, s24
	s_lshl_b32 s11, s7, 7
	s_add_u32 s11, s11, s47
	v_and_b32_e32 v239, 1, v249
	v_lshrrev_b32_e32 v240, 1, v249
	v_lshlrev_b32_e32 v239, 4, v239
	v_lshl_add_u32 v239, v240, 3, v239
	v_add_u32_e32 v239, s11, v239
	v_lshlrev_b32_e32 v239, 1, v239
	v_add_u32_e32 v230, v230, v239
	s_lshl_b32 s11, s24, 4
	v_add_u32_e32 v231, s11, v230
	v_add_u32_e32 v232, s11, v231
	v_add_u32_e32 v233, s11, v232
	s_nop 7
	v_add_u32_e32 v239, s33, v242
	ds_read_b32 v234, v239
	ds_read_b32 v235, v239 offset:64
	ds_read_b32 v236, v239 offset:128
	ds_read_b32 v237, v239 offset:192
	s_waitcnt lgkmcnt(0)
	v_mul_f32_e32 v0, v0, v234
	v_mul_f32_e32 v1, v1, v234
	v_mul_f32_e32 v2, v2, v234
	v_mul_f32_e32 v3, v3, v234
	v_mul_f32_e32 v4, v4, v234
	v_mul_f32_e32 v5, v5, v234
	v_mul_f32_e32 v6, v6, v234
	v_mul_f32_e32 v7, v7, v234
	v_mul_f32_e32 v32, v32, v235
	v_mul_f32_e32 v33, v33, v235
	v_mul_f32_e32 v34, v34, v235
	v_mul_f32_e32 v35, v35, v235
	v_mul_f32_e32 v36, v36, v235
	v_mul_f32_e32 v37, v37, v235
	v_mul_f32_e32 v38, v38, v235
	v_mul_f32_e32 v39, v39, v235
	v_mul_f32_e32 v64, v64, v236
	v_mul_f32_e32 v65, v65, v236
	v_mul_f32_e32 v66, v66, v236
	v_mul_f32_e32 v67, v67, v236
	v_mul_f32_e32 v68, v68, v236
	v_mul_f32_e32 v69, v69, v236
	v_mul_f32_e32 v70, v70, v236
	v_mul_f32_e32 v71, v71, v236
	v_mul_f32_e32 v96, v96, v237
	v_mul_f32_e32 v97, v97, v237
	v_mul_f32_e32 v98, v98, v237
	v_mul_f32_e32 v99, v99, v237
	v_mul_f32_e32 v100, v100, v237
	v_mul_f32_e32 v101, v101, v237
	v_mul_f32_e32 v102, v102, v237
	v_mul_f32_e32 v103, v103, v237
	s_cmp_eq_u32 s30, 0
	s_cbranch_scc1 .Lgw_norelu
	v_max_f32_e32 v0, 0, v0
	v_mul_f32_e32 v0, v0, v0
	v_max_f32_e32 v1, 0, v1
	v_mul_f32_e32 v1, v1, v1
	v_max_f32_e32 v2, 0, v2
	v_mul_f32_e32 v2, v2, v2
	v_max_f32_e32 v3, 0, v3
	v_mul_f32_e32 v3, v3, v3
	v_max_f32_e32 v4, 0, v4
	v_mul_f32_e32 v4, v4, v4
	v_max_f32_e32 v5, 0, v5
	v_mul_f32_e32 v5, v5, v5
	v_max_f32_e32 v6, 0, v6
	v_mul_f32_e32 v6, v6, v6
	v_max_f32_e32 v7, 0, v7
	v_mul_f32_e32 v7, v7, v7
	v_max_f32_e32 v32, 0, v32
	v_mul_f32_e32 v32, v32, v32
	v_max_f32_e32 v33, 0, v33
	v_mul_f32_e32 v33, v33, v33
	v_max_f32_e32 v34, 0, v34
	v_mul_f32_e32 v34, v34, v34
	v_max_f32_e32 v35, 0, v35
	v_mul_f32_e32 v35, v35, v35
	v_max_f32_e32 v36, 0, v36
	v_mul_f32_e32 v36, v36, v36
	v_max_f32_e32 v37, 0, v37
	v_mul_f32_e32 v37, v37, v37
	v_max_f32_e32 v38, 0, v38
	v_mul_f32_e32 v38, v38, v38
	v_max_f32_e32 v39, 0, v39
	v_mul_f32_e32 v39, v39, v39
	v_max_f32_e32 v64, 0, v64
	v_mul_f32_e32 v64, v64, v64
	v_max_f32_e32 v65, 0, v65
	v_mul_f32_e32 v65, v65, v65
	v_max_f32_e32 v66, 0, v66
	v_mul_f32_e32 v66, v66, v66
	v_max_f32_e32 v67, 0, v67
	v_mul_f32_e32 v67, v67, v67
	v_max_f32_e32 v68, 0, v68
	v_mul_f32_e32 v68, v68, v68
	v_max_f32_e32 v69, 0, v69
	v_mul_f32_e32 v69, v69, v69
	v_max_f32_e32 v70, 0, v70
	v_mul_f32_e32 v70, v70, v70
	v_max_f32_e32 v71, 0, v71
	v_mul_f32_e32 v71, v71, v71
	v_max_f32_e32 v96, 0, v96
	v_mul_f32_e32 v96, v96, v96
	v_max_f32_e32 v97, 0, v97
	v_mul_f32_e32 v97, v97, v97
	v_max_f32_e32 v98, 0, v98
	v_mul_f32_e32 v98, v98, v98
	v_max_f32_e32 v99, 0, v99
	v_mul_f32_e32 v99, v99, v99
	v_max_f32_e32 v100, 0, v100
	v_mul_f32_e32 v100, v100, v100
	v_max_f32_e32 v101, 0, v101
	v_mul_f32_e32 v101, v101, v101
	v_max_f32_e32 v102, 0, v102
	v_mul_f32_e32 v102, v102, v102
	v_max_f32_e32 v103, 0, v103
	v_mul_f32_e32 v103, v103, v103
.Lgw_norelu:
	v_cvt_pk_bf16_f32 v0, v0, v1
	v_cvt_pk_bf16_f32 v1, v2, v3
	v_cvt_pk_bf16_f32 v2, v4, v5
	v_cvt_pk_bf16_f32 v3, v6, v7
	s_nop 1
	v_permlane16_swap_b32_e32 v0, v2
	v_permlane16_swap_b32_e32 v1, v3
	global_store_dwordx4 v230, v[0:3], s[22:23]
	v_cvt_pk_bf16_f32 v32, v32, v33
	v_cvt_pk_bf16_f32 v33, v34, v35
	v_cvt_pk_bf16_f32 v34, v36, v37
	v_cvt_pk_bf16_f32 v35, v38, v39
	s_nop 1
	v_permlane16_swap_b32_e32 v32, v34
	v_permlane16_swap_b32_e32 v33, v35
	global_store_dwordx4 v231, v[32:35], s[22:23]
	v_cvt_pk_bf16_f32 v64, v64, v65
	v_cvt_pk_bf16_f32 v65, v66, v67
	v_cvt_pk_bf16_f32 v66, v68, v69
	v_cvt_pk_bf16_f32 v67, v70, v71
	s_nop 1
	v_permlane16_swap_b32_e32 v64, v66
	v_permlane16_swap_b32_e32 v65, v67
	global_store_dwordx4 v232, v[64:67], s[22:23]
	v_cvt_pk_bf16_f32 v96, v96, v97
	v_cvt_pk_bf16_f32 v97, v98, v99
	v_cvt_pk_bf16_f32 v98, v100, v101
	v_cvt_pk_bf16_f32 v99, v102, v103
	s_nop 1
	v_permlane16_swap_b32_e32 v96, v98
	v_permlane16_swap_b32_e32 v97, v99
	global_store_dwordx4 v233, v[96:99], s[22:23]
	s_xor_b32 s33, s33, 0x400

; template <int EPI>
; __device__ __forceinline__ void gemm_phase(const Params& p, const u16* __restrict__ A, int lda, const u16* __restrict__ BT, int ldb,
;                            int K, int N, u16* __restrict__ outb, int ldo, int resid_in, int boff) {
;     ...
;   for (int un = bstart; un < units; un += G) {
;     int tl = un, kbeg = 0, KT = KTALL;
;     bool part_unit = false;
;     if (un >= t_full) { const int v = un - t_full; tl = t_full + v / split; KT = KTALL / split; kbeg = (v % split) * KT; part_unit = true; }
;     int mt = tl / NT, nt = tl % NT;
;     if (EPI == EPI_RES && NT == 8 && G == 256 && !part_unit) {
;       const int rr = tl >> 8, bb = tl & 255;
;       const int xx = bb & 7, jj = bb >> 3;
;       mt = rr * 32 + xx * 4 + (jj >> 3);
;       nt = jj & 7;
;     } else if ((EPI == EPI_FF1 || EPI == EPI_SCALE) && G == 256 && (NT == 32 || NT == 16) && tl < (tiles & ~255)) {
;       const int rr = tl >> 8, bb = tl & 255;
;       const int xx = bb & 7, jj = bb >> 3;
;       if (NT == 32) { mt = rr * 8 + (xx >> 2) * 4 + (jj >> 3); nt = (xx & 3) * 8 + (jj & 7); }
;       else { mt = rr * 16 + (xx >> 1) * 4 + (jj >> 3); nt = (xx & 1) * 8 + (jj & 7); }
;     }
.Lgp_cnt_done:
	s_mov_b32 s11, 0
	s_mov_b32 s18, 0
	s_cmp_ge_u32 s5, s38
	s_cbranch_scc1 .Lgp_su_done_p0
	s_mov_b32 s47, 0
	s_cmp_ge_u32 s5, s28
	s_cbranch_scc1 .Lgm_split_p0
	s_mov_b32 s8, 0
	s_mov_b32 s9, s39
	s_mov_b32 s10, 0
	s_cmp_eq_u32 s27, 0
	s_cbranch_scc1 .Lgm_plain_p0
	s_cmp_ge_u32 s5, s29
	s_cbranch_scc1 .Lgm_plain_p0
	s_lshr_b32 s6, s5, 8
	s_and_b32 s7, s5, 0xff
	s_and_b32 s36, s7, 7
	s_lshr_b32 s37, s7, 3
	s_cmp_eq_u32 s27, 3
	s_cbranch_scc1 .Lgm_map8_p0
	s_cmp_eq_u32 s27, 1
	s_cbranch_scc0 .Lgm_map16_p0
	s_lshl_b32 s6, s6, 3
	s_lshr_b32 s7, s36, 2
	s_lshl_b32 s7, s7, 2
	s_add_u32 s6, s6, s7
	s_lshr_b32 s7, s37, 3
	s_add_u32 s6, s6, s7
	s_and_b32 s7, s36, 3
	s_lshl_b32 s7, s7, 3
	s_and_b32 s37, s37, 7
	s_add_u32 s7, s7, s37
	s_branch .Lgm_dec_done_p0

; template <int EPI>
; __device__ __forceinline__ void gemm_phase(const Params& p, const u16* __restrict__ A, int lda, const u16* __restrict__ BT, int ldb,
;                            int K, int N, u16* __restrict__ outb, int ldo, int resid_in, int boff) {
;     ...
;     const int m0 = mt * 256, n0 = nt * 128;
;     const u16* gA = A + (size_t)(m0 + lrow) * lda + lch * 8 + (size_t)kbeg * 64;
;     const u16* gB = BT + (size_t)(n0 + lrow) * ldb + lch * 8 + (size_t)kbeg * 64;
.Lgm_dec_done_p0:
	s_mov_b32 s11, 1
	s_mov_b32 s18, s9
	s_add_u32 s36, s45, 8
	s_lshl_b32 s36, s6, s36
	s_lshl_b32 s37, s8, 7
	s_add_u32 s36, s36, s37
	s_add_u32 s0, s16, s36
	s_addc_u32 s1, s17, 0
	s_add_u32 s36, s46, 7
	s_lshl_b32 s36, s7, s36
	s_add_u32 s36, s36, s37
	s_add_u32 s2, s20, s36
	s_addc_u32 s3, s21, 0
	s_cmp_lg_u32 s10, 2
	s_cbranch_scc1 .Lgp_su_nn_p0
	s_lshl_b32 s36, s4, 5
	s_sub_u32 s36, s47, s36
	s_ashr_i32 s37, s36, 31
	s_lshl_b64 s[36:37], s[36:37], s46
	s_add_u32 s2, s2, s36
	s_addc_u32 s3, s3, s37
.Lgp_su_nn_p0:
	s_cmp_ge_u32 s30, 3
	s_cbranch_scc1 .Lgp_su_done_p0
	s_mov_b32 s12, 1
	s_lshl_b32 s36, s6, 8
	v_add_u32_e32 v160, s36, v165
	v_lshlrev_b32_e32 v160, 6, v160

; template <int EPI>
; __device__ __forceinline__ void gemm_phase(const Params& p, const u16* __restrict__ A, int lda, const u16* __restrict__ BT, int ldb,
;                            int K, int N, u16* __restrict__ outb, int ldo, int resid_in, int boff) {
;     ...
;   for (int un = bstart; un < units; un += G) {
;     int tl = un, kbeg = 0, KT = KTALL;
;     bool part_unit = false;
;     if (un >= t_full) { const int v = un - t_full; tl = t_full + v / split; KT = KTALL / split; kbeg = (v % split) * KT; part_unit = true; }
;     int mt = tl / NT, nt = tl % NT;
;     if (EPI == EPI_RES && NT == 8 && G == 256 && !part_unit) {
;       const int rr = tl >> 8, bb = tl & 255;
;       const int xx = bb & 7, jj = bb >> 3;
;       mt = rr * 32 + xx * 4 + (jj >> 3);
;       nt = jj & 7;
;     } else if ((EPI == EPI_FF1 || EPI == EPI_SCALE) && G == 256 && (NT == 32 || NT == 16) && tl < (tiles & ~255)) {
;       const int rr = tl >> 8, bb = tl & 255;
;       const int xx = bb & 7, jj = bb >> 3;
;       if (NT == 32) { mt = rr * 8 + (xx >> 2) * 4 + (jj >> 3); nt = (xx & 3) * 8 + (jj & 7); }
;       else { mt = rr * 16 + (xx >> 1) * 4 + (jj >> 3); nt = (xx & 1) * 8 + (jj & 7); }
;     }
.Lgp_is_nop_pa:
	s_add_u32 m0, s31, s32
	s_nop 0
	global_load_lds_dwordx4 v130, s[0:1]
	s_add_u32 m0, m0, 0x400
	s_nop 0
	global_load_lds_dwordx4 v131, s[0:1]
	s_add_u32 m0, m0, 0x400
	s_nop 0
	global_load_lds_dwordx4 v132, s[0:1]
	s_add_u32 m0, m0, 0x400
	s_nop 0
	global_load_lds_dwordx4 v133, s[0:1]
	s_add_u32 m0, m0, 0x400
	s_nop 0
	global_load_lds_dwordx4 v134, s[0:1]
	s_add_u32 m0, m0, 0x400
	s_nop 0
	global_load_lds_dwordx4 v135, s[0:1]
	s_add_u32 m0, m0, 0x400
	s_nop 0
	global_load_lds_dwordx4 v136, s[0:1]
	s_add_u32 m0, m0, 0x400
	s_nop 0
	global_load_lds_dwordx4 v137, s[0:1]
	s_add_u32 m0, s31, s34
	s_nop 0
	global_load_lds_dwordx4 v138, s[2:3]
	s_add_u32 m0, m0, 0x400
	s_nop 0
	global_load_lds_dwordx4 v139, s[2:3]
	s_add_u32 m0, m0, 0x400
	s_nop 0
	global_load_lds_dwordx4 v140, s[2:3]
	s_add_u32 m0, m0, 0x400
	s_nop 0
	global_load_lds_dwordx4 v141, s[2:3]
	s_add_u32 s0, s0, 0x80
	s_addc_u32 s1, s1, 0
	s_add_u32 s2, s2, 0x80
	s_addc_u32 s3, s3, 0
	s_add_u32 s31, s31, 0xc000
	s_cmp_eq_u32 s31, 0x24000
	s_cselect_b32 s31, 0, s31
	s_sub_u32 s18, s18, 1
	s_cmp_lg_u32 s18, 0
	s_cbranch_scc1 .Lgp_is_done_pa
	s_add_u32 s5, s5, s42
	s_mov_b32 s13, s10
	s_mov_b32 s11, 0
	s_mov_b32 s18, 0
	s_cmp_ge_u32 s5, s38
	s_cbranch_scc1 .Lgp_su_done_pau
	s_mov_b32 s47, 0
	s_cmp_ge_u32 s5, s28
	s_cbranch_scc1 .Lgm_split_pau
	s_mov_b32 s8, 0
	s_mov_b32 s9, s39
	s_mov_b32 s10, 0
	s_cmp_eq_u32 s27, 0
	s_cbranch_scc1 .Lgm_plain_pau
	s_cmp_ge_u32 s5, s29
	s_cbranch_scc1 .Lgm_plain_pau
	s_lshr_b32 s6, s5, 8
	s_and_b32 s7, s5, 0xff
	s_and_b32 s36, s7, 7
	s_lshr_b32 s37, s7, 3
	s_cmp_eq_u32 s27, 3
	s_cbranch_scc1 .Lgm_map8_pau
	s_cmp_eq_u32 s27, 1
	s_cbranch_scc0 .Lgm_map16_pau
	s_lshl_b32 s6, s6, 3
	s_lshr_b32 s7, s36, 2
	s_lshl_b32 s7, s7, 2
	s_add_u32 s6, s6, s7
	s_lshr_b32 s7, s37, 3
	s_add_u32 s6, s6, s7
	s_and_b32 s7, s36, 3
	s_lshl_b32 s7, s7, 3
	s_and_b32 s37, s37, 7
	s_add_u32 s7, s7, s37
	s_branch .Lgm_dec_done_pau
